# MLA: second max chain interleaved with the PV MFMAs (waves 4-7: behind their barrier) so only the rescale test is left at the end of the tile
# baseline (speedup 1.0000x reference)
; __device__ __forceinline__ void finishSM9(f32x16& p0, f32x16& p1, float alpha, float& l_reg, v8i32& p8) {
; #pragma unroll
;   for (int r = 0; r < 16; ++r) { p0[r] = __builtin_amdgcn_exp2f(p0[r]); p1[r] = __builtin_amdgcn_exp2f(p1[r]); }
;   float ps = 0;
; #pragma unroll
;   for (int r = 0; r < 16; ++r) ps += p0[r];
; #pragma unroll
;   for (int r = 0; r < 16; ++r) ps += p1[r];
;   { auto rr = __builtin_amdgcn_permlane32_swap(__float_as_uint(ps), __float_as_uint(ps), false, false);
;     ps = __uint_as_float(rr[0]) + __uint_as_float(rr[1]); }
;   l_reg = l_reg * alpha + ps;
; #pragma unroll
;   for (int g = 0; g < 4; ++g) {
;     int w = __builtin_amdgcn_cvt_pk_fp8_f32(p0[4 * g], p0[4 * g + 1], 0, false); p8[g] = __builtin_amdgcn_cvt_pk_fp8_f32(p0[4 * g + 2], p0[4 * g + 3], w, true);
;     int u = __builtin_amdgcn_cvt_pk_fp8_f32(p1[4 * g], p1[4 * g + 1], 0, false); p8[4 + g] = __builtin_amdgcn_cvt_pk_fp8_f32(p1[4 * g + 2], p1[4 * g + 3], u, true); }
; }
; __device__ __forceinline__ void pv8(f32x16* o, const char* Vt, const v8i32 p8, int r32, int hi) {
;   const int sw = (r32 >> 2) & 3, a0 = r32 * 64 + (((hi * 2) ^ sw) << 4), a1 = r32 * 64 + (((hi * 2 + 1) ^ sw) << 4);
; #pragma unroll
;   for (int d0 = 0; d0 < 4; ++d0) {
;     const v8i32 vf = cat8(*reinterpret_cast<const v4i32*>(Vt + d0 * 2048 + a0), *reinterpret_cast<const v4i32*>(Vt + d0 * 2048 + a1));
;     o[d0] = __builtin_amdgcn_mfma_scale_f32_32x32x64_f8f6f4(p8, vf, o[d0], 0, 0, 0, 127, 0, 127); }
; }
; __device__ __forceinline__ void qkt9(f32x16& p0, f32x16& p1, const char* Kn, const char* Kr, const v8i32* qf, const float init, int r32, int hi) {
; #pragma unroll
;   for (int r = 0; r < 16; ++r) { p0[r] = init; p1[r] = init; }
; #pragma unroll
;   for (int s = 0; s < 2; ++s) { const int c0 = s * 4 + hi * 2;
;     const v8i32 a0 = cat8(*reinterpret_cast<const v4i32*>(Kn + KN8SW(r32, c0)), *reinterpret_cast<const v4i32*>(Kn + KN8SW(r32, c0 + 1)));
;     const v8i32 a1 = cat8(*reinterpret_cast<const v4i32*>(Kn + 4096 + KN8SW(r32, c0)), *reinterpret_cast<const v4i32*>(Kn + 4096 + KN8SW(r32, c0 + 1)));
;     p0 = __builtin_amdgcn_mfma_scale_f32_32x32x64_f8f6f4(a0, qf[s], p0, 0, 0, 0, 127, 0, 124);
;     p1 = __builtin_amdgcn_mfma_scale_f32_32x32x64_f8f6f4(a1, qf[s], p1, 0, 0, 0, 127, 0, 124); }
;   { const int c0 = hi * 2;
.Lmla_stag_loop:
	ds_read_b128 v[114:117], v215 offset:24576
	ds_read_b128 v[118:121], v216 offset:24576
	ds_read_b128 v[222:225], v215 offset:28672
	ds_read_b128 v[226:229], v216 offset:28672
	v_exp_f32_e32 v0, v82
	v_exp_f32_e32 v177, v83
	v_exp_f32_e32 v179, v84
	v_exp_f32_e32 v254, v85
	v_add_f32_e32 v219, v0, v177
	v_cvt_pk_fp8_f32 v246, v0, v177
	v_add_f32_e32 v219, v179, v219
	v_add_f32_e32 v219, v254, v219
	v_cvt_pk_fp8_f32 v246, v179, v254 op_sel:[0,0,1]
	s_waitcnt lgkmcnt(2)
	v_mfma_scale_f32_32x32x64_f8f6f4 v[114:129], v[114:121], v[146:153], v[230:245], v194, v193 op_sel_hi:[0,0,0]
	v_exp_f32_e32 v0, v86
	v_exp_f32_e32 v177, v87
	v_exp_f32_e32 v179, v88
	v_exp_f32_e32 v254, v89
	v_add_f32_e32 v219, v0, v219
	v_add_f32_e32 v219, v177, v219
	v_cvt_pk_fp8_f32 v247, v0, v177
	v_add_f32_e32 v219, v179, v219
	v_add_f32_e32 v219, v254, v219
	v_cvt_pk_fp8_f32 v247, v179, v254 op_sel:[0,0,1]
	ds_read_b128 v[82:85], v213 offset:24576
	ds_read_b128 v[86:89], v214 offset:24576
	s_waitcnt lgkmcnt(2)
	v_mfma_scale_f32_32x32x64_f8f6f4 v[98:113], v[222:229], v[146:153], v[230:245], v194, v193 op_sel_hi:[0,0,0]
	ds_read_b128 v[222:225], v213 offset:28672
	ds_read_b128 v[226:229], v214 offset:28672
	v_exp_f32_e32 v0, v90
	v_exp_f32_e32 v177, v91
	v_exp_f32_e32 v179, v92
	v_exp_f32_e32 v254, v93
	v_add_f32_e32 v219, v0, v219
	v_add_f32_e32 v219, v177, v219
	v_cvt_pk_fp8_f32 v248, v0, v177
	v_add_f32_e32 v219, v179, v219
	v_add_f32_e32 v219, v254, v219
	v_cvt_pk_fp8_f32 v248, v179, v254 op_sel:[0,0,1]
	v_exp_f32_e32 v0, v94
	v_exp_f32_e32 v177, v95
	v_exp_f32_e32 v179, v96
	v_exp_f32_e32 v254, v97
	v_add_f32_e32 v219, v0, v219
	v_add_f32_e32 v219, v177, v219
	v_cvt_pk_fp8_f32 v249, v0, v177
	v_add_f32_e32 v219, v179, v219
	v_add_f32_e32 v219, v254, v219
	v_cvt_pk_fp8_f32 v249, v179, v254 op_sel:[0,0,1]
	ds_read_b128 v[90:93], v185 offset:36864
	ds_read_b128 v[94:97], v186 offset:36864
	s_waitcnt lgkmcnt(4)
	v_mfma_scale_f32_32x32x64_f8f6f4 v[114:129], v[82:89], v[138:145], v[114:129], v194, v193 op_sel_hi:[0,0,0]
	v_exp_f32_e32 v0, v66
	v_exp_f32_e32 v177, v67
	v_exp_f32_e32 v179, v68
	v_exp_f32_e32 v254, v69
	v_add_f32_e32 v219, v0, v219
	v_add_f32_e32 v219, v177, v219
	v_cvt_pk_fp8_f32 v250, v0, v177
	v_add_f32_e32 v219, v179, v219
	v_add_f32_e32 v219, v254, v219
	v_cvt_pk_fp8_f32 v250, v179, v254 op_sel:[0,0,1]
	s_waitcnt lgkmcnt(2)
	v_mfma_scale_f32_32x32x64_f8f6f4 v[98:113], v[222:229], v[138:145], v[98:113], v194, v193 op_sel_hi:[0,0,0]
	ds_read_b128 v[222:225], v185 offset:38912
	ds_read_b128 v[226:229], v186 offset:38912
	v_exp_f32_e32 v0, v70
	v_exp_f32_e32 v177, v71
	v_exp_f32_e32 v179, v72
	v_exp_f32_e32 v254, v73
	v_add_f32_e32 v219, v0, v219
	v_add_f32_e32 v219, v177, v219
	v_cvt_pk_fp8_f32 v251, v0, v177
	v_add_f32_e32 v219, v179, v219
	v_add_f32_e32 v219, v254, v219
	v_cvt_pk_fp8_f32 v251, v179, v254 op_sel:[0,0,1]
	v_exp_f32_e32 v0, v74
	v_exp_f32_e32 v177, v75
	v_exp_f32_e32 v179, v76
	v_exp_f32_e32 v254, v77
	v_add_f32_e32 v219, v0, v219
	v_add_f32_e32 v219, v177, v219
	v_cvt_pk_fp8_f32 v252, v0, v177
	v_add_f32_e32 v219, v179, v219
	v_add_f32_e32 v219, v254, v219
	v_cvt_pk_fp8_f32 v252, v179, v254 op_sel:[0,0,1]
	s_waitcnt lgkmcnt(2)
	v_mfma_scale_f32_32x32x64_f8f6f4 v[114:129], v[90:97], v[130:137], v[114:129], v194, v193 op_sel_hi:[0,0,0]
	v_exp_f32_e32 v0, v78
	v_exp_f32_e32 v177, v79
	v_exp_f32_e32 v179, v80
	v_exp_f32_e32 v254, v81
	v_add_f32_e32 v219, v0, v219
	v_add_f32_e32 v219, v177, v219
	v_cvt_pk_fp8_f32 v253, v0, v177
	v_add_f32_e32 v219, v179, v219
	v_add_f32_e32 v219, v254, v219
	v_cvt_pk_fp8_f32 v253, v179, v254 op_sel:[0,0,1]
	ds_read_b128 v[90:93], v185 offset:0
	ds_read_b128 v[94:97], v186 offset:0
	ds_read_b128 v[82:85], v185 offset:2048
	ds_read_b128 v[86:89], v186 offset:2048
	ds_read_b128 v[74:77], v185 offset:4096
	ds_read_b128 v[78:81], v186 offset:4096
	ds_read_b128 v[66:69], v185 offset:6144
	ds_read_b128 v[70:73], v186 offset:6144
	s_waitcnt lgkmcnt(8)
	v_mfma_scale_f32_32x32x64_f8f6f4 v[98:113], v[222:229], v[130:137], v[98:113], v194, v193 op_sel_hi:[0,0,0]
	v_mov_b32_e32 v0, v219
	s_nop 1
	v_permlane32_swap_b32_e32 v219, v0
	v_add_f32_e32 v219, v219, v0
	v_fma_f32 v209, v209, v218, v219
	v_max_f32_e32 v177, v114, v115
	v_max3_f32 v177, v177, v116, v117
	v_max3_f32 v177, v177, v118, v119
	v_max3_f32 v177, v177, v120, v121
	v_max3_f32 v177, v177, v122, v123
	v_max3_f32 v177, v177, v124, v125
	v_max3_f32 v177, v177, v126, v127
	v_max3_f32 v177, v177, v128, v129
	s_waitcnt lgkmcnt(6)
	v_mfma_scale_f32_32x32x64_f8f6f4 v[50:65], v[246:253], v[90:97], v[50:65], v194, v194 op_sel_hi:[0,0,0]
	s_waitcnt vmcnt(0)
	ds_write_b128 v210, v[158:161] offset:43008
	ds_write_b128 v211, v[162:165] offset:51200
	s_waitcnt lgkmcnt(6)
	v_mfma_scale_f32_32x32x64_f8f6f4 v[34:49], v[246:253], v[82:89], v[34:49], v194, v194 op_sel_hi:[0,0,0]
	s_waitcnt lgkmcnt(0)
	s_barrier
	global_load_dwordx4 v[158:161], v176, s[18:19]
	global_load_dwordx4 v[162:165], v178, s[16:17]
	v_add_u32_e32 v176, 0x2000, v176
	v_add_u32_e32 v178, 0x20000, v178
	v_max_f32_e32 v0, v98, v99
	v_max3_f32 v0, v0, v100, v101
	v_max3_f32 v0, v0, v102, v103
	v_max3_f32 v0, v0, v104, v105
	s_waitcnt lgkmcnt(2)
	v_mfma_scale_f32_32x32x64_f8f6f4 v[18:33], v[246:253], v[74:81], v[18:33], v194, v194 op_sel_hi:[0,0,0]
	v_max3_f32 v0, v0, v106, v107
	v_max3_f32 v0, v0, v108, v109
	v_max3_f32 v0, v0, v110, v111
	v_max3_f32 v0, v0, v112, v113
	s_waitcnt lgkmcnt(0)
	v_mfma_scale_f32_32x32x64_f8f6f4 v[2:17], v[246:253], v[66:73], v[2:17], v194, v194 op_sel_hi:[0,0,0]
	v_max_f32_e32 v177, v177, v0
	v_mov_b32_e32 v0, v177
	v_mov_b32_e32 v221, 1.0
	s_nop 0
	v_permlane32_swap_b32_e32 v177, v0
	v_max_f32_e32 v177, v177, v0
	v_cmp_ge_f32_e32 vcc, s90, v177
	s_cmp_eq_u64 vcc, exec
	s_cbranch_scc0 .Lmla_s0_newmax
; __device__ __forceinline__ void finishSM9(f32x16& p0, f32x16& p1, float alpha, float& l_reg, v8i32& p8) {
; #pragma unroll
;   for (int r = 0; r < 16; ++r) { p0[r] = __builtin_amdgcn_exp2f(p0[r]); p1[r] = __builtin_amdgcn_exp2f(p1[r]); }
;   float ps = 0;
; #pragma unroll
;   for (int r = 0; r < 16; ++r) ps += p0[r];
; #pragma unroll
;   for (int r = 0; r < 16; ++r) ps += p1[r];
;   { auto rr = __builtin_amdgcn_permlane32_swap(__float_as_uint(ps), __float_as_uint(ps), false, false);
;     ps = __uint_as_float(rr[0]) + __uint_as_float(rr[1]); }
;   l_reg = l_reg * alpha + ps;
; #pragma unroll
;   for (int g = 0; g < 4; ++g) {
;     int w = __builtin_amdgcn_cvt_pk_fp8_f32(p0[4 * g], p0[4 * g + 1], 0, false); p8[g] = __builtin_amdgcn_cvt_pk_fp8_f32(p0[4 * g + 2], p0[4 * g + 3], w, true);
;     int u = __builtin_amdgcn_cvt_pk_fp8_f32(p1[4 * g], p1[4 * g + 1], 0, false); p8[4 + g] = __builtin_amdgcn_cvt_pk_fp8_f32(p1[4 * g + 2], p1[4 * g + 3], u, true); }
; }
; __device__ __forceinline__ void pv8(f32x16* o, const char* Vt, const v8i32 p8, int r32, int hi) {
;   const int sw = (r32 >> 2) & 3, a0 = r32 * 64 + (((hi * 2) ^ sw) << 4), a1 = r32 * 64 + (((hi * 2 + 1) ^ sw) << 4);
; #pragma unroll
;   for (int d0 = 0; d0 < 4; ++d0) {
;     const v8i32 vf = cat8(*reinterpret_cast<const v4i32*>(Vt + d0 * 2048 + a0), *reinterpret_cast<const v4i32*>(Vt + d0 * 2048 + a1));
;     o[d0] = __builtin_amdgcn_mfma_scale_f32_32x32x64_f8f6f4(p8, vf, o[d0], 0, 0, 0, 127, 0, 127); }
; }
; __device__ __forceinline__ void qkt9(f32x16& p0, f32x16& p1, const char* Kn, const char* Kr, const v8i32* qf, const float init, int r32, int hi) {
; #pragma unroll
;   for (int r = 0; r < 16; ++r) { p0[r] = init; p1[r] = init; }
; #pragma unroll
;   for (int s = 0; s < 2; ++s) { const int c0 = s * 4 + hi * 2;
;     const v8i32 a0 = cat8(*reinterpret_cast<const v4i32*>(Kn + KN8SW(r32, c0)), *reinterpret_cast<const v4i32*>(Kn + KN8SW(r32, c0 + 1)));
;     const v8i32 a1 = cat8(*reinterpret_cast<const v4i32*>(Kn + 4096 + KN8SW(r32, c0)), *reinterpret_cast<const v4i32*>(Kn + 4096 + KN8SW(r32, c0 + 1)));
;     p0 = __builtin_amdgcn_mfma_scale_f32_32x32x64_f8f6f4(a0, qf[s], p0, 0, 0, 0, 127, 0, 124);
;     p1 = __builtin_amdgcn_mfma_scale_f32_32x32x64_f8f6f4(a1, qf[s], p1, 0, 0, 0, 127, 0, 124); }
;   { const int c0 = hi * 2;
.Lmla_s0_cont:
	ds_read_b128 v[82:85], v215 offset:51200
	ds_read_b128 v[86:89], v216 offset:51200
	ds_read_b128 v[222:225], v215 offset:55296
	ds_read_b128 v[226:229], v216 offset:55296
	v_exp_f32_e32 v0, v114
	v_exp_f32_e32 v177, v115
	v_exp_f32_e32 v179, v116
	v_exp_f32_e32 v254, v117
	v_add_f32_e32 v219, v0, v177
	v_cvt_pk_fp8_f32 v246, v0, v177
	v_add_f32_e32 v219, v179, v219
	v_add_f32_e32 v219, v254, v219
	v_cvt_pk_fp8_f32 v246, v179, v254 op_sel:[0,0,1]
	s_waitcnt lgkmcnt(2)
	v_mfma_scale_f32_32x32x64_f8f6f4 v[82:97], v[82:89], v[146:153], v[230:245], v194, v193 op_sel_hi:[0,0,0]
	v_exp_f32_e32 v0, v118
	v_exp_f32_e32 v177, v119
	v_exp_f32_e32 v179, v120
	v_exp_f32_e32 v254, v121
	v_add_f32_e32 v219, v0, v219
	v_add_f32_e32 v219, v177, v219
	v_cvt_pk_fp8_f32 v247, v0, v177
	v_add_f32_e32 v219, v179, v219
	v_add_f32_e32 v219, v254, v219
	v_cvt_pk_fp8_f32 v247, v179, v254 op_sel:[0,0,1]
	ds_read_b128 v[114:117], v213 offset:51200
	ds_read_b128 v[118:121], v214 offset:51200
	s_waitcnt lgkmcnt(2)
	v_mfma_scale_f32_32x32x64_f8f6f4 v[66:81], v[222:229], v[146:153], v[230:245], v194, v193 op_sel_hi:[0,0,0]
	ds_read_b128 v[222:225], v213 offset:55296
	ds_read_b128 v[226:229], v214 offset:55296
	v_exp_f32_e32 v0, v122
	v_exp_f32_e32 v177, v123
	v_exp_f32_e32 v179, v124
	v_exp_f32_e32 v254, v125
	v_add_f32_e32 v219, v0, v219
	v_add_f32_e32 v219, v177, v219
	v_cvt_pk_fp8_f32 v248, v0, v177
	v_add_f32_e32 v219, v179, v219
	v_add_f32_e32 v219, v254, v219
	v_cvt_pk_fp8_f32 v248, v179, v254 op_sel:[0,0,1]
	v_exp_f32_e32 v0, v126
	v_exp_f32_e32 v177, v127
	v_exp_f32_e32 v179, v128
	v_exp_f32_e32 v254, v129
	v_add_f32_e32 v219, v0, v219
	v_add_f32_e32 v219, v177, v219
	v_cvt_pk_fp8_f32 v249, v0, v177
	v_add_f32_e32 v219, v179, v219
	v_add_f32_e32 v219, v254, v219
	v_cvt_pk_fp8_f32 v249, v179, v254 op_sel:[0,0,1]
	ds_read_b128 v[122:125], v185 offset:59392
	ds_read_b128 v[126:129], v186 offset:59392
	s_waitcnt lgkmcnt(4)
	v_mfma_scale_f32_32x32x64_f8f6f4 v[82:97], v[114:121], v[138:145], v[82:97], v194, v193 op_sel_hi:[0,0,0]
	v_exp_f32_e32 v0, v98
	v_exp_f32_e32 v177, v99
	v_exp_f32_e32 v179, v100
	v_exp_f32_e32 v254, v101
	v_add_f32_e32 v219, v0, v219
	v_add_f32_e32 v219, v177, v219
	v_cvt_pk_fp8_f32 v250, v0, v177
	v_add_f32_e32 v219, v179, v219
	v_add_f32_e32 v219, v254, v219
	v_cvt_pk_fp8_f32 v250, v179, v254 op_sel:[0,0,1]
	s_waitcnt lgkmcnt(2)
	v_mfma_scale_f32_32x32x64_f8f6f4 v[66:81], v[222:229], v[138:145], v[66:81], v194, v193 op_sel_hi:[0,0,0]
	ds_read_b128 v[222:225], v185 offset:61440
	ds_read_b128 v[226:229], v186 offset:61440
	v_exp_f32_e32 v0, v102
	v_exp_f32_e32 v177, v103
	v_exp_f32_e32 v179, v104
	v_exp_f32_e32 v254, v105
	v_add_f32_e32 v219, v0, v219
	v_add_f32_e32 v219, v177, v219
	v_cvt_pk_fp8_f32 v251, v0, v177
	v_add_f32_e32 v219, v179, v219
	v_add_f32_e32 v219, v254, v219
	v_cvt_pk_fp8_f32 v251, v179, v254 op_sel:[0,0,1]
	v_exp_f32_e32 v0, v106
	v_exp_f32_e32 v177, v107
	v_exp_f32_e32 v179, v108
	v_exp_f32_e32 v254, v109
	v_add_f32_e32 v219, v0, v219
	v_add_f32_e32 v219, v177, v219
	v_cvt_pk_fp8_f32 v252, v0, v177
	v_add_f32_e32 v219, v179, v219
	v_add_f32_e32 v219, v254, v219
	v_cvt_pk_fp8_f32 v252, v179, v254 op_sel:[0,0,1]
	s_waitcnt lgkmcnt(2)
	v_mfma_scale_f32_32x32x64_f8f6f4 v[82:97], v[122:129], v[130:137], v[82:97], v194, v193 op_sel_hi:[0,0,0]
	v_exp_f32_e32 v0, v110
	v_exp_f32_e32 v177, v111
	v_exp_f32_e32 v179, v112
	v_exp_f32_e32 v254, v113
	v_add_f32_e32 v219, v0, v219
	v_add_f32_e32 v219, v177, v219
	v_cvt_pk_fp8_f32 v253, v0, v177
	v_add_f32_e32 v219, v179, v219
	v_add_f32_e32 v219, v254, v219
	v_cvt_pk_fp8_f32 v253, v179, v254 op_sel:[0,0,1]
	ds_read_b128 v[122:125], v185 offset:8192
	ds_read_b128 v[126:129], v186 offset:8192
	ds_read_b128 v[114:117], v185 offset:10240
	ds_read_b128 v[118:121], v186 offset:10240
	ds_read_b128 v[106:109], v185 offset:12288
	ds_read_b128 v[110:113], v186 offset:12288
	ds_read_b128 v[98:101], v185 offset:14336
	ds_read_b128 v[102:105], v186 offset:14336
	s_waitcnt lgkmcnt(8)
	v_mfma_scale_f32_32x32x64_f8f6f4 v[66:81], v[222:229], v[130:137], v[66:81], v194, v193 op_sel_hi:[0,0,0]
	v_mov_b32_e32 v0, v219
	s_nop 1
	v_permlane32_swap_b32_e32 v219, v0
	v_add_f32_e32 v219, v219, v0
	v_fma_f32 v209, v209, v221, v219
	v_max_f32_e32 v177, v82, v83
	v_max3_f32 v177, v177, v84, v85
	v_max3_f32 v177, v177, v86, v87
	v_max3_f32 v177, v177, v88, v89
	v_max3_f32 v177, v177, v90, v91
	v_max3_f32 v177, v177, v92, v93
	v_max3_f32 v177, v177, v94, v95
	v_max3_f32 v177, v177, v96, v97
	s_waitcnt lgkmcnt(6)
	v_mfma_scale_f32_32x32x64_f8f6f4 v[50:65], v[246:253], v[122:129], v[50:65], v194, v194 op_sel_hi:[0,0,0]
	s_waitcnt vmcnt(0)
	ds_write_b128 v210, v[158:161]
	ds_write_b128 v211, v[162:165] offset:16384
	s_waitcnt lgkmcnt(6)
	v_mfma_scale_f32_32x32x64_f8f6f4 v[34:49], v[246:253], v[114:121], v[34:49], v194, v194 op_sel_hi:[0,0,0]
	s_waitcnt lgkmcnt(0)
	s_barrier
	global_load_dwordx4 v[158:161], v176, s[18:19]
	global_load_dwordx4 v[162:165], v178, s[16:17]
	v_add_u32_e32 v176, 0x2000, v176
	v_add_u32_e32 v178, 0x20000, v178
	v_max_f32_e32 v0, v66, v67
	v_max3_f32 v0, v0, v68, v69
	v_max3_f32 v0, v0, v70, v71
	v_max3_f32 v0, v0, v72, v73
	s_waitcnt lgkmcnt(2)
	v_mfma_scale_f32_32x32x64_f8f6f4 v[18:33], v[246:253], v[106:113], v[18:33], v194, v194 op_sel_hi:[0,0,0]
	v_max3_f32 v0, v0, v74, v75
	v_max3_f32 v0, v0, v76, v77
	v_max3_f32 v0, v0, v78, v79
	v_max3_f32 v0, v0, v80, v81
	s_waitcnt lgkmcnt(0)
	v_mfma_scale_f32_32x32x64_f8f6f4 v[2:17], v[246:253], v[98:105], v[2:17], v194, v194 op_sel_hi:[0,0,0]
	v_max_f32_e32 v177, v177, v0
	v_mov_b32_e32 v0, v177
	v_mov_b32_e32 v218, 1.0
	s_nop 0
	v_permlane32_swap_b32_e32 v177, v0
	v_max_f32_e32 v177, v177, v0
	v_cmp_ge_f32_e32 vcc, s90, v177
	s_cmp_eq_u64 vcc, exec
	s_cbranch_scc0 .Lmla_s1_newmax
; __device__ __forceinline__ void finishSM9(f32x16& p0, f32x16& p1, float alpha, float& l_reg, v8i32& p8) {
; #pragma unroll
;   for (int r = 0; r < 16; ++r) { p0[r] = __builtin_amdgcn_exp2f(p0[r]); p1[r] = __builtin_amdgcn_exp2f(p1[r]); }
;   float ps = 0;
; #pragma unroll
;   for (int r = 0; r < 16; ++r) ps += p0[r];
; #pragma unroll
;   for (int r = 0; r < 16; ++r) ps += p1[r];
;   { auto rr = __builtin_amdgcn_permlane32_swap(__float_as_uint(ps), __float_as_uint(ps), false, false);
;     ps = __uint_as_float(rr[0]) + __uint_as_float(rr[1]); }
;   l_reg = l_reg * alpha + ps;
; #pragma unroll
;   for (int g = 0; g < 4; ++g) {
;     int w = __builtin_amdgcn_cvt_pk_fp8_f32(p0[4 * g], p0[4 * g + 1], 0, false); p8[g] = __builtin_amdgcn_cvt_pk_fp8_f32(p0[4 * g + 2], p0[4 * g + 3], w, true);
;     int u = __builtin_amdgcn_cvt_pk_fp8_f32(p1[4 * g], p1[4 * g + 1], 0, false); p8[4 + g] = __builtin_amdgcn_cvt_pk_fp8_f32(p1[4 * g + 2], p1[4 * g + 3], u, true); }
; }
; __device__ __forceinline__ void pv8(f32x16* o, const char* Vt, const v8i32 p8, int r32, int hi) {
;   const int sw = (r32 >> 2) & 3, a0 = r32 * 64 + (((hi * 2) ^ sw) << 4), a1 = r32 * 64 + (((hi * 2 + 1) ^ sw) << 4);
; #pragma unroll
;   for (int d0 = 0; d0 < 4; ++d0) {
;     const v8i32 vf = cat8(*reinterpret_cast<const v4i32*>(Vt + d0 * 2048 + a0), *reinterpret_cast<const v4i32*>(Vt + d0 * 2048 + a1));
;     o[d0] = __builtin_amdgcn_mfma_scale_f32_32x32x64_f8f6f4(p8, vf, o[d0], 0, 0, 0, 127, 0, 127); }
; }
; __device__ __forceinline__ void qkt9(f32x16& p0, f32x16& p1, const char* Kn, const char* Kr, const v8i32* qf, const float init, int r32, int hi) {
; #pragma unroll
;   for (int r = 0; r < 16; ++r) { p0[r] = init; p1[r] = init; }
; #pragma unroll
;   for (int s = 0; s < 2; ++s) { const int c0 = s * 4 + hi * 2;
;     const v8i32 a0 = cat8(*reinterpret_cast<const v4i32*>(Kn + KN8SW(r32, c0)), *reinterpret_cast<const v4i32*>(Kn + KN8SW(r32, c0 + 1)));
;     const v8i32 a1 = cat8(*reinterpret_cast<const v4i32*>(Kn + 4096 + KN8SW(r32, c0)), *reinterpret_cast<const v4i32*>(Kn + 4096 + KN8SW(r32, c0 + 1)));
;     p0 = __builtin_amdgcn_mfma_scale_f32_32x32x64_f8f6f4(a0, qf[s], p0, 0, 0, 0, 127, 0, 124);
;     p1 = __builtin_amdgcn_mfma_scale_f32_32x32x64_f8f6f4(a1, qf[s], p1, 0, 0, 0, 127, 0, 124); }
;   { const int c0 = hi * 2;
.Lmla_s1_cont:
	ds_read_b128 v[114:117], v215 offset:16384
	ds_read_b128 v[118:121], v216 offset:16384
	ds_read_b128 v[222:225], v215 offset:20480
	ds_read_b128 v[226:229], v216 offset:20480
	v_exp_f32_e32 v0, v82
	v_exp_f32_e32 v177, v83
	v_exp_f32_e32 v179, v84
	v_exp_f32_e32 v254, v85
	v_add_f32_e32 v219, v0, v177
	v_cvt_pk_fp8_f32 v246, v0, v177
	v_add_f32_e32 v219, v179, v219
	v_add_f32_e32 v219, v254, v219
	v_cvt_pk_fp8_f32 v246, v179, v254 op_sel:[0,0,1]
	s_waitcnt lgkmcnt(2)
	v_mfma_scale_f32_32x32x64_f8f6f4 v[114:129], v[114:121], v[146:153], v[230:245], v194, v193 op_sel_hi:[0,0,0]
	v_exp_f32_e32 v0, v86
	v_exp_f32_e32 v177, v87
	v_exp_f32_e32 v179, v88
	v_exp_f32_e32 v254, v89
	v_add_f32_e32 v219, v0, v219
	v_add_f32_e32 v219, v177, v219
	v_cvt_pk_fp8_f32 v247, v0, v177
	v_add_f32_e32 v219, v179, v219
	v_add_f32_e32 v219, v254, v219
	v_cvt_pk_fp8_f32 v247, v179, v254 op_sel:[0,0,1]
	ds_read_b128 v[82:85], v213 offset:16384
	ds_read_b128 v[86:89], v214 offset:16384
	s_waitcnt lgkmcnt(2)
	v_mfma_scale_f32_32x32x64_f8f6f4 v[98:113], v[222:229], v[146:153], v[230:245], v194, v193 op_sel_hi:[0,0,0]
	ds_read_b128 v[222:225], v213 offset:20480
	ds_read_b128 v[226:229], v214 offset:20480
	v_exp_f32_e32 v0, v90
	v_exp_f32_e32 v177, v91
	v_exp_f32_e32 v179, v92
	v_exp_f32_e32 v254, v93
	v_add_f32_e32 v219, v0, v219
	v_add_f32_e32 v219, v177, v219
	v_cvt_pk_fp8_f32 v248, v0, v177
	v_add_f32_e32 v219, v179, v219
	v_add_f32_e32 v219, v254, v219
	v_cvt_pk_fp8_f32 v248, v179, v254 op_sel:[0,0,1]
	v_exp_f32_e32 v0, v94
	v_exp_f32_e32 v177, v95
	v_exp_f32_e32 v179, v96
	v_exp_f32_e32 v254, v97
	v_add_f32_e32 v219, v0, v219
	v_add_f32_e32 v219, v177, v219
	v_cvt_pk_fp8_f32 v249, v0, v177
	v_add_f32_e32 v219, v179, v219
	v_add_f32_e32 v219, v254, v219
	v_cvt_pk_fp8_f32 v249, v179, v254 op_sel:[0,0,1]
	ds_read_b128 v[90:93], v185 offset:32768
	ds_read_b128 v[94:97], v186 offset:32768
	s_waitcnt lgkmcnt(4)
	v_mfma_scale_f32_32x32x64_f8f6f4 v[114:129], v[82:89], v[138:145], v[114:129], v194, v193 op_sel_hi:[0,0,0]
	v_exp_f32_e32 v0, v66
	v_exp_f32_e32 v177, v67
	v_exp_f32_e32 v179, v68
	v_exp_f32_e32 v254, v69
	v_add_f32_e32 v219, v0, v219
	v_add_f32_e32 v219, v177, v219
	v_cvt_pk_fp8_f32 v250, v0, v177
	v_add_f32_e32 v219, v179, v219
	v_add_f32_e32 v219, v254, v219
	v_cvt_pk_fp8_f32 v250, v179, v254 op_sel:[0,0,1]
	s_waitcnt lgkmcnt(2)
	v_mfma_scale_f32_32x32x64_f8f6f4 v[98:113], v[222:229], v[138:145], v[98:113], v194, v193 op_sel_hi:[0,0,0]
	ds_read_b128 v[222:225], v185 offset:34816
	ds_read_b128 v[226:229], v186 offset:34816
	v_exp_f32_e32 v0, v70
	v_exp_f32_e32 v177, v71
	v_exp_f32_e32 v179, v72
	v_exp_f32_e32 v254, v73
	v_add_f32_e32 v219, v0, v219
	v_add_f32_e32 v219, v177, v219
	v_cvt_pk_fp8_f32 v251, v0, v177
	v_add_f32_e32 v219, v179, v219
	v_add_f32_e32 v219, v254, v219
	v_cvt_pk_fp8_f32 v251, v179, v254 op_sel:[0,0,1]
	v_exp_f32_e32 v0, v74
	v_exp_f32_e32 v177, v75
	v_exp_f32_e32 v179, v76
	v_exp_f32_e32 v254, v77
	v_add_f32_e32 v219, v0, v219
	v_add_f32_e32 v219, v177, v219
	v_cvt_pk_fp8_f32 v252, v0, v177
	v_add_f32_e32 v219, v179, v219
	v_add_f32_e32 v219, v254, v219
	v_cvt_pk_fp8_f32 v252, v179, v254 op_sel:[0,0,1]
	s_waitcnt lgkmcnt(2)
	v_mfma_scale_f32_32x32x64_f8f6f4 v[114:129], v[90:97], v[130:137], v[114:129], v194, v193 op_sel_hi:[0,0,0]
	v_exp_f32_e32 v0, v78
	v_exp_f32_e32 v177, v79
	v_exp_f32_e32 v179, v80
	v_exp_f32_e32 v254, v81
	v_add_f32_e32 v219, v0, v219
	v_add_f32_e32 v219, v177, v219
	v_cvt_pk_fp8_f32 v253, v0, v177
	v_add_f32_e32 v219, v179, v219
	v_add_f32_e32 v219, v254, v219
	v_cvt_pk_fp8_f32 v253, v179, v254 op_sel:[0,0,1]
	ds_read_b128 v[90:93], v185 offset:43008
	ds_read_b128 v[94:97], v186 offset:43008
	ds_read_b128 v[82:85], v185 offset:45056
	ds_read_b128 v[86:89], v186 offset:45056
	ds_read_b128 v[74:77], v185 offset:47104
	ds_read_b128 v[78:81], v186 offset:47104
	ds_read_b128 v[66:69], v185 offset:49152
	ds_read_b128 v[70:73], v186 offset:49152
	s_waitcnt lgkmcnt(8)
	v_mfma_scale_f32_32x32x64_f8f6f4 v[98:113], v[222:229], v[130:137], v[98:113], v194, v193 op_sel_hi:[0,0,0]
	v_mov_b32_e32 v0, v219
	s_nop 1
	v_permlane32_swap_b32_e32 v219, v0
	v_add_f32_e32 v219, v219, v0
	v_fma_f32 v209, v209, v218, v219
	v_max_f32_e32 v177, v114, v115
	v_max3_f32 v177, v177, v116, v117
	v_max3_f32 v177, v177, v118, v119
	v_max3_f32 v177, v177, v120, v121
	v_max3_f32 v177, v177, v122, v123
	v_max3_f32 v177, v177, v124, v125
	v_max3_f32 v177, v177, v126, v127
	v_max3_f32 v177, v177, v128, v129
	s_waitcnt lgkmcnt(6)
	v_mfma_scale_f32_32x32x64_f8f6f4 v[50:65], v[246:253], v[90:97], v[50:65], v194, v194 op_sel_hi:[0,0,0]
	s_waitcnt vmcnt(0)
	ds_write_b128 v210, v[158:161] offset:8192
	ds_write_b128 v211, v[162:165] offset:24576
	s_waitcnt lgkmcnt(6)
	v_mfma_scale_f32_32x32x64_f8f6f4 v[34:49], v[246:253], v[82:89], v[34:49], v194, v194 op_sel_hi:[0,0,0]
	s_waitcnt lgkmcnt(0)
	s_barrier
	global_load_dwordx4 v[158:161], v176, s[18:19]
	global_load_dwordx4 v[162:165], v178, s[16:17]
	v_add_u32_e32 v176, 0x2000, v176
	v_add_u32_e32 v178, 0x20000, v178
	v_max_f32_e32 v0, v98, v99
	v_max3_f32 v0, v0, v100, v101
	v_max3_f32 v0, v0, v102, v103
	v_max3_f32 v0, v0, v104, v105
	s_waitcnt lgkmcnt(2)
	v_mfma_scale_f32_32x32x64_f8f6f4 v[18:33], v[246:253], v[74:81], v[18:33], v194, v194 op_sel_hi:[0,0,0]
	v_max3_f32 v0, v0, v106, v107
	v_max3_f32 v0, v0, v108, v109
	v_max3_f32 v0, v0, v110, v111
	v_max3_f32 v0, v0, v112, v113
	s_waitcnt lgkmcnt(0)
	v_mfma_scale_f32_32x32x64_f8f6f4 v[2:17], v[246:253], v[66:73], v[2:17], v194, v194 op_sel_hi:[0,0,0]
	v_max_f32_e32 v177, v177, v0
	v_mov_b32_e32 v0, v177
	v_mov_b32_e32 v221, 1.0
	s_nop 0
	v_permlane32_swap_b32_e32 v177, v0
	v_max_f32_e32 v177, v177, v0
	v_cmp_ge_f32_e32 vcc, s90, v177
	s_cmp_eq_u64 vcc, exec
	s_cbranch_scc0 .Lmla_s2_newmax
; __device__ __forceinline__ void finishSM9(f32x16& p0, f32x16& p1, float alpha, float& l_reg, v8i32& p8) {
; #pragma unroll
;   for (int r = 0; r < 16; ++r) { p0[r] = __builtin_amdgcn_exp2f(p0[r]); p1[r] = __builtin_amdgcn_exp2f(p1[r]); }
;   float ps = 0;
; #pragma unroll
;   for (int r = 0; r < 16; ++r) ps += p0[r];
; #pragma unroll
;   for (int r = 0; r < 16; ++r) ps += p1[r];
;   { auto rr = __builtin_amdgcn_permlane32_swap(__float_as_uint(ps), __float_as_uint(ps), false, false);
;     ps = __uint_as_float(rr[0]) + __uint_as_float(rr[1]); }
;   l_reg = l_reg * alpha + ps;
; #pragma unroll
;   for (int g = 0; g < 4; ++g) {
;     int w = __builtin_amdgcn_cvt_pk_fp8_f32(p0[4 * g], p0[4 * g + 1], 0, false); p8[g] = __builtin_amdgcn_cvt_pk_fp8_f32(p0[4 * g + 2], p0[4 * g + 3], w, true);
;     int u = __builtin_amdgcn_cvt_pk_fp8_f32(p1[4 * g], p1[4 * g + 1], 0, false); p8[4 + g] = __builtin_amdgcn_cvt_pk_fp8_f32(p1[4 * g + 2], p1[4 * g + 3], u, true); }
; }
; __device__ __forceinline__ void pv8(f32x16* o, const char* Vt, const v8i32 p8, int r32, int hi) {
;   const int sw = (r32 >> 2) & 3, a0 = r32 * 64 + (((hi * 2) ^ sw) << 4), a1 = r32 * 64 + (((hi * 2 + 1) ^ sw) << 4);
; #pragma unroll
;   for (int d0 = 0; d0 < 4; ++d0) {
;     const v8i32 vf = cat8(*reinterpret_cast<const v4i32*>(Vt + d0 * 2048 + a0), *reinterpret_cast<const v4i32*>(Vt + d0 * 2048 + a1));
;     o[d0] = __builtin_amdgcn_mfma_scale_f32_32x32x64_f8f6f4(p8, vf, o[d0], 0, 0, 0, 127, 0, 127); }
; }
; __device__ __forceinline__ void qkt9(f32x16& p0, f32x16& p1, const char* Kn, const char* Kr, const v8i32* qf, const float init, int r32, int hi) {
; #pragma unroll
;   for (int r = 0; r < 16; ++r) { p0[r] = init; p1[r] = init; }
; #pragma unroll
;   for (int s = 0; s < 2; ++s) { const int c0 = s * 4 + hi * 2;
;     const v8i32 a0 = cat8(*reinterpret_cast<const v4i32*>(Kn + KN8SW(r32, c0)), *reinterpret_cast<const v4i32*>(Kn + KN8SW(r32, c0 + 1)));
;     const v8i32 a1 = cat8(*reinterpret_cast<const v4i32*>(Kn + 4096 + KN8SW(r32, c0)), *reinterpret_cast<const v4i32*>(Kn + 4096 + KN8SW(r32, c0 + 1)));
;     p0 = __builtin_amdgcn_mfma_scale_f32_32x32x64_f8f6f4(a0, qf[s], p0, 0, 0, 0, 127, 0, 124);
;     p1 = __builtin_amdgcn_mfma_scale_f32_32x32x64_f8f6f4(a1, qf[s], p1, 0, 0, 0, 127, 0, 124); }
;   { const int c0 = hi * 2;
.Lmla_s2_cont:
	ds_read_b128 v[82:85], v215 offset:24576
	ds_read_b128 v[86:89], v216 offset:24576
	ds_read_b128 v[222:225], v215 offset:28672
	ds_read_b128 v[226:229], v216 offset:28672
	v_exp_f32_e32 v0, v114
	v_exp_f32_e32 v177, v115
	v_exp_f32_e32 v179, v116
	v_exp_f32_e32 v254, v117
	v_add_f32_e32 v219, v0, v177
	v_cvt_pk_fp8_f32 v246, v0, v177
	v_add_f32_e32 v219, v179, v219
	v_add_f32_e32 v219, v254, v219
	v_cvt_pk_fp8_f32 v246, v179, v254 op_sel:[0,0,1]
	s_waitcnt lgkmcnt(2)
	v_mfma_scale_f32_32x32x64_f8f6f4 v[82:97], v[82:89], v[146:153], v[230:245], v194, v193 op_sel_hi:[0,0,0]
	v_exp_f32_e32 v0, v118
	v_exp_f32_e32 v177, v119
	v_exp_f32_e32 v179, v120
	v_exp_f32_e32 v254, v121
	v_add_f32_e32 v219, v0, v219
	v_add_f32_e32 v219, v177, v219
	v_cvt_pk_fp8_f32 v247, v0, v177
	v_add_f32_e32 v219, v179, v219
	v_add_f32_e32 v219, v254, v219
	v_cvt_pk_fp8_f32 v247, v179, v254 op_sel:[0,0,1]
	ds_read_b128 v[114:117], v213 offset:24576
	ds_read_b128 v[118:121], v214 offset:24576
	s_waitcnt lgkmcnt(2)
	v_mfma_scale_f32_32x32x64_f8f6f4 v[66:81], v[222:229], v[146:153], v[230:245], v194, v193 op_sel_hi:[0,0,0]
	ds_read_b128 v[222:225], v213 offset:28672
	ds_read_b128 v[226:229], v214 offset:28672
	v_exp_f32_e32 v0, v122
	v_exp_f32_e32 v177, v123
	v_exp_f32_e32 v179, v124
	v_exp_f32_e32 v254, v125
	v_add_f32_e32 v219, v0, v219
	v_add_f32_e32 v219, v177, v219
	v_cvt_pk_fp8_f32 v248, v0, v177
	v_add_f32_e32 v219, v179, v219
	v_add_f32_e32 v219, v254, v219
	v_cvt_pk_fp8_f32 v248, v179, v254 op_sel:[0,0,1]
	v_exp_f32_e32 v0, v126
	v_exp_f32_e32 v177, v127
	v_exp_f32_e32 v179, v128
	v_exp_f32_e32 v254, v129
	v_add_f32_e32 v219, v0, v219
	v_add_f32_e32 v219, v177, v219
	v_cvt_pk_fp8_f32 v249, v0, v177
	v_add_f32_e32 v219, v179, v219
	v_add_f32_e32 v219, v254, v219
	v_cvt_pk_fp8_f32 v249, v179, v254 op_sel:[0,0,1]
	ds_read_b128 v[122:125], v185 offset:36864
	ds_read_b128 v[126:129], v186 offset:36864
	s_waitcnt lgkmcnt(4)
	v_mfma_scale_f32_32x32x64_f8f6f4 v[82:97], v[114:121], v[138:145], v[82:97], v194, v193 op_sel_hi:[0,0,0]
	v_exp_f32_e32 v0, v98
	v_exp_f32_e32 v177, v99
	v_exp_f32_e32 v179, v100
	v_exp_f32_e32 v254, v101
	v_add_f32_e32 v219, v0, v219
	v_add_f32_e32 v219, v177, v219
	v_cvt_pk_fp8_f32 v250, v0, v177
	v_add_f32_e32 v219, v179, v219
	v_add_f32_e32 v219, v254, v219
	v_cvt_pk_fp8_f32 v250, v179, v254 op_sel:[0,0,1]
	s_waitcnt lgkmcnt(2)
	v_mfma_scale_f32_32x32x64_f8f6f4 v[66:81], v[222:229], v[138:145], v[66:81], v194, v193 op_sel_hi:[0,0,0]
	ds_read_b128 v[222:225], v185 offset:38912
	ds_read_b128 v[226:229], v186 offset:38912
	v_exp_f32_e32 v0, v102
	v_exp_f32_e32 v177, v103
	v_exp_f32_e32 v179, v104
	v_exp_f32_e32 v254, v105
	v_add_f32_e32 v219, v0, v219
	v_add_f32_e32 v219, v177, v219
	v_cvt_pk_fp8_f32 v251, v0, v177
	v_add_f32_e32 v219, v179, v219
	v_add_f32_e32 v219, v254, v219
	v_cvt_pk_fp8_f32 v251, v179, v254 op_sel:[0,0,1]
	v_exp_f32_e32 v0, v106
	v_exp_f32_e32 v177, v107
	v_exp_f32_e32 v179, v108
	v_exp_f32_e32 v254, v109
	v_add_f32_e32 v219, v0, v219
	v_add_f32_e32 v219, v177, v219
	v_cvt_pk_fp8_f32 v252, v0, v177
	v_add_f32_e32 v219, v179, v219
	v_add_f32_e32 v219, v254, v219
	v_cvt_pk_fp8_f32 v252, v179, v254 op_sel:[0,0,1]
	s_waitcnt lgkmcnt(2)
	v_mfma_scale_f32_32x32x64_f8f6f4 v[82:97], v[122:129], v[130:137], v[82:97], v194, v193 op_sel_hi:[0,0,0]
	v_exp_f32_e32 v0, v110
	v_exp_f32_e32 v177, v111
	v_exp_f32_e32 v179, v112
	v_exp_f32_e32 v254, v113
	v_add_f32_e32 v219, v0, v219
	v_add_f32_e32 v219, v177, v219
	v_cvt_pk_fp8_f32 v253, v0, v177
	v_add_f32_e32 v219, v179, v219
	v_add_f32_e32 v219, v254, v219
	v_cvt_pk_fp8_f32 v253, v179, v254 op_sel:[0,0,1]
	ds_read_b128 v[122:125], v185 offset:0
	ds_read_b128 v[126:129], v186 offset:0
	ds_read_b128 v[114:117], v185 offset:2048
	ds_read_b128 v[118:121], v186 offset:2048
	ds_read_b128 v[106:109], v185 offset:4096
	ds_read_b128 v[110:113], v186 offset:4096
	ds_read_b128 v[98:101], v185 offset:6144
	ds_read_b128 v[102:105], v186 offset:6144
	s_waitcnt lgkmcnt(8)
	v_mfma_scale_f32_32x32x64_f8f6f4 v[66:81], v[222:229], v[130:137], v[66:81], v194, v193 op_sel_hi:[0,0,0]
	v_mov_b32_e32 v0, v219
	s_nop 1
	v_permlane32_swap_b32_e32 v219, v0
	v_add_f32_e32 v219, v219, v0
	v_fma_f32 v209, v209, v221, v219
	v_max_f32_e32 v177, v82, v83
	v_max3_f32 v177, v177, v84, v85
	v_max3_f32 v177, v177, v86, v87
	v_max3_f32 v177, v177, v88, v89
	v_max3_f32 v177, v177, v90, v91
	v_max3_f32 v177, v177, v92, v93
	v_max3_f32 v177, v177, v94, v95
	v_max3_f32 v177, v177, v96, v97
	s_waitcnt lgkmcnt(6)
	v_mfma_scale_f32_32x32x64_f8f6f4 v[50:65], v[246:253], v[122:129], v[50:65], v194, v194 op_sel_hi:[0,0,0]
	s_waitcnt vmcnt(0)
	ds_write_b128 v210, v[158:161] offset:43008
	ds_write_b128 v211, v[162:165] offset:51200
	s_waitcnt lgkmcnt(6)
	v_mfma_scale_f32_32x32x64_f8f6f4 v[34:49], v[246:253], v[114:121], v[34:49], v194, v194 op_sel_hi:[0,0,0]
	s_waitcnt lgkmcnt(0)
	s_barrier
	global_load_dwordx4 v[158:161], v176, s[18:19]
	global_load_dwordx4 v[162:165], v178, s[16:17]
	v_add_u32_e32 v176, 0x2000, v176
	v_add_u32_e32 v178, 0x20000, v178
	v_max_f32_e32 v0, v66, v67
	v_max3_f32 v0, v0, v68, v69
	v_max3_f32 v0, v0, v70, v71
	v_max3_f32 v0, v0, v72, v73
	s_waitcnt lgkmcnt(2)
	v_mfma_scale_f32_32x32x64_f8f6f4 v[18:33], v[246:253], v[106:113], v[18:33], v194, v194 op_sel_hi:[0,0,0]
	v_max3_f32 v0, v0, v74, v75
	v_max3_f32 v0, v0, v76, v77
	v_max3_f32 v0, v0, v78, v79
	v_max3_f32 v0, v0, v80, v81
	s_waitcnt lgkmcnt(0)
	v_mfma_scale_f32_32x32x64_f8f6f4 v[2:17], v[246:253], v[98:105], v[2:17], v194, v194 op_sel_hi:[0,0,0]
	v_max_f32_e32 v177, v177, v0
	v_mov_b32_e32 v0, v177
	v_mov_b32_e32 v218, 1.0
	s_nop 0
	v_permlane32_swap_b32_e32 v177, v0
	v_max_f32_e32 v177, v177, v0
	v_cmp_ge_f32_e32 vcc, s90, v177
	s_cmp_eq_u64 vcc, exec
	s_cbranch_scc0 .Lmla_s3_newmax
; __device__ __forceinline__ void finishSM9(f32x16& p0, f32x16& p1, float alpha, float& l_reg, v8i32& p8) {
; #pragma unroll
;   for (int r = 0; r < 16; ++r) { p0[r] = __builtin_amdgcn_exp2f(p0[r]); p1[r] = __builtin_amdgcn_exp2f(p1[r]); }
;   float ps = 0;
; #pragma unroll
;   for (int r = 0; r < 16; ++r) ps += p0[r];
; #pragma unroll
;   for (int r = 0; r < 16; ++r) ps += p1[r];
;   { auto rr = __builtin_amdgcn_permlane32_swap(__float_as_uint(ps), __float_as_uint(ps), false, false);
;     ps = __uint_as_float(rr[0]) + __uint_as_float(rr[1]); }
;   l_reg = l_reg * alpha + ps;
; #pragma unroll
;   for (int g = 0; g < 4; ++g) {
;     int w = __builtin_amdgcn_cvt_pk_fp8_f32(p0[4 * g], p0[4 * g + 1], 0, false); p8[g] = __builtin_amdgcn_cvt_pk_fp8_f32(p0[4 * g + 2], p0[4 * g + 3], w, true);
;     int u = __builtin_amdgcn_cvt_pk_fp8_f32(p1[4 * g], p1[4 * g + 1], 0, false); p8[4 + g] = __builtin_amdgcn_cvt_pk_fp8_f32(p1[4 * g + 2], p1[4 * g + 3], u, true); }
; }
; __device__ __forceinline__ void pv8(f32x16* o, const char* Vt, const v8i32 p8, int r32, int hi) {
;   const int sw = (r32 >> 2) & 3, a0 = r32 * 64 + (((hi * 2) ^ sw) << 4), a1 = r32 * 64 + (((hi * 2 + 1) ^ sw) << 4);
; #pragma unroll
;   for (int d0 = 0; d0 < 4; ++d0) {
;     const v8i32 vf = cat8(*reinterpret_cast<const v4i32*>(Vt + d0 * 2048 + a0), *reinterpret_cast<const v4i32*>(Vt + d0 * 2048 + a1));
;     o[d0] = __builtin_amdgcn_mfma_scale_f32_32x32x64_f8f6f4(p8, vf, o[d0], 0, 0, 0, 127, 0, 127); }
; }
; __device__ __forceinline__ void qkt9(f32x16& p0, f32x16& p1, const char* Kn, const char* Kr, const v8i32* qf, const float init, int r32, int hi) {
; #pragma unroll
;   for (int r = 0; r < 16; ++r) { p0[r] = init; p1[r] = init; }
; #pragma unroll
;   for (int s = 0; s < 2; ++s) { const int c0 = s * 4 + hi * 2;
;     const v8i32 a0 = cat8(*reinterpret_cast<const v4i32*>(Kn + KN8SW(r32, c0)), *reinterpret_cast<const v4i32*>(Kn + KN8SW(r32, c0 + 1)));
;     const v8i32 a1 = cat8(*reinterpret_cast<const v4i32*>(Kn + 4096 + KN8SW(r32, c0)), *reinterpret_cast<const v4i32*>(Kn + 4096 + KN8SW(r32, c0 + 1)));
;     p0 = __builtin_amdgcn_mfma_scale_f32_32x32x64_f8f6f4(a0, qf[s], p0, 0, 0, 0, 127, 0, 124);
;     p1 = __builtin_amdgcn_mfma_scale_f32_32x32x64_f8f6f4(a1, qf[s], p1, 0, 0, 0, 127, 0, 124); }
;   { const int c0 = hi * 2;
.Lmla_s3_cont:
	ds_read_b128 v[114:117], v215 offset:51200
	ds_read_b128 v[118:121], v216 offset:51200
	ds_read_b128 v[222:225], v215 offset:55296
	ds_read_b128 v[226:229], v216 offset:55296
	v_exp_f32_e32 v0, v82
	v_exp_f32_e32 v177, v83
	v_exp_f32_e32 v179, v84
	v_exp_f32_e32 v254, v85
	v_add_f32_e32 v219, v0, v177
	v_cvt_pk_fp8_f32 v246, v0, v177
	v_add_f32_e32 v219, v179, v219
	v_add_f32_e32 v219, v254, v219
	v_cvt_pk_fp8_f32 v246, v179, v254 op_sel:[0,0,1]
	s_waitcnt lgkmcnt(2)
	v_mfma_scale_f32_32x32x64_f8f6f4 v[114:129], v[114:121], v[146:153], v[230:245], v194, v193 op_sel_hi:[0,0,0]
	v_exp_f32_e32 v0, v86
	v_exp_f32_e32 v177, v87
	v_exp_f32_e32 v179, v88
	v_exp_f32_e32 v254, v89
	v_add_f32_e32 v219, v0, v219
	v_add_f32_e32 v219, v177, v219
	v_cvt_pk_fp8_f32 v247, v0, v177
	v_add_f32_e32 v219, v179, v219
	v_add_f32_e32 v219, v254, v219
	v_cvt_pk_fp8_f32 v247, v179, v254 op_sel:[0,0,1]
	ds_read_b128 v[82:85], v213 offset:51200
	ds_read_b128 v[86:89], v214 offset:51200
	s_waitcnt lgkmcnt(2)
	v_mfma_scale_f32_32x32x64_f8f6f4 v[98:113], v[222:229], v[146:153], v[230:245], v194, v193 op_sel_hi:[0,0,0]
	ds_read_b128 v[222:225], v213 offset:55296
	ds_read_b128 v[226:229], v214 offset:55296
	v_exp_f32_e32 v0, v90
	v_exp_f32_e32 v177, v91
	v_exp_f32_e32 v179, v92
	v_exp_f32_e32 v254, v93
	v_add_f32_e32 v219, v0, v219
	v_add_f32_e32 v219, v177, v219
	v_cvt_pk_fp8_f32 v248, v0, v177
	v_add_f32_e32 v219, v179, v219
	v_add_f32_e32 v219, v254, v219
	v_cvt_pk_fp8_f32 v248, v179, v254 op_sel:[0,0,1]
	v_exp_f32_e32 v0, v94
	v_exp_f32_e32 v177, v95
	v_exp_f32_e32 v179, v96
	v_exp_f32_e32 v254, v97
	v_add_f32_e32 v219, v0, v219
	v_add_f32_e32 v219, v177, v219
	v_cvt_pk_fp8_f32 v249, v0, v177
	v_add_f32_e32 v219, v179, v219
	v_add_f32_e32 v219, v254, v219
	v_cvt_pk_fp8_f32 v249, v179, v254 op_sel:[0,0,1]
	ds_read_b128 v[90:93], v185 offset:59392
	ds_read_b128 v[94:97], v186 offset:59392
	s_waitcnt lgkmcnt(4)
	v_mfma_scale_f32_32x32x64_f8f6f4 v[114:129], v[82:89], v[138:145], v[114:129], v194, v193 op_sel_hi:[0,0,0]
	v_exp_f32_e32 v0, v66
	v_exp_f32_e32 v177, v67
	v_exp_f32_e32 v179, v68
	v_exp_f32_e32 v254, v69
	v_add_f32_e32 v219, v0, v219
	v_add_f32_e32 v219, v177, v219
	v_cvt_pk_fp8_f32 v250, v0, v177
	v_add_f32_e32 v219, v179, v219
	v_add_f32_e32 v219, v254, v219
	v_cvt_pk_fp8_f32 v250, v179, v254 op_sel:[0,0,1]
	s_waitcnt lgkmcnt(2)
	v_mfma_scale_f32_32x32x64_f8f6f4 v[98:113], v[222:229], v[138:145], v[98:113], v194, v193 op_sel_hi:[0,0,0]
	ds_read_b128 v[222:225], v185 offset:61440
	ds_read_b128 v[226:229], v186 offset:61440
	v_exp_f32_e32 v0, v70
	v_exp_f32_e32 v177, v71
	v_exp_f32_e32 v179, v72
	v_exp_f32_e32 v254, v73
	v_add_f32_e32 v219, v0, v219
	v_add_f32_e32 v219, v177, v219
	v_cvt_pk_fp8_f32 v251, v0, v177
	v_add_f32_e32 v219, v179, v219
	v_add_f32_e32 v219, v254, v219
	v_cvt_pk_fp8_f32 v251, v179, v254 op_sel:[0,0,1]
	v_exp_f32_e32 v0, v74
	v_exp_f32_e32 v177, v75
	v_exp_f32_e32 v179, v76
	v_exp_f32_e32 v254, v77
	v_add_f32_e32 v219, v0, v219
	v_add_f32_e32 v219, v177, v219
	v_cvt_pk_fp8_f32 v252, v0, v177
	v_add_f32_e32 v219, v179, v219
	v_add_f32_e32 v219, v254, v219
	v_cvt_pk_fp8_f32 v252, v179, v254 op_sel:[0,0,1]
	s_waitcnt lgkmcnt(2)
	v_mfma_scale_f32_32x32x64_f8f6f4 v[114:129], v[90:97], v[130:137], v[114:129], v194, v193 op_sel_hi:[0,0,0]
	v_exp_f32_e32 v0, v78
	v_exp_f32_e32 v177, v79
	v_exp_f32_e32 v179, v80
	v_exp_f32_e32 v254, v81
	v_add_f32_e32 v219, v0, v219
	v_add_f32_e32 v219, v177, v219
	v_cvt_pk_fp8_f32 v253, v0, v177
	v_add_f32_e32 v219, v179, v219
	v_add_f32_e32 v219, v254, v219
	v_cvt_pk_fp8_f32 v253, v179, v254 op_sel:[0,0,1]
	ds_read_b128 v[90:93], v185 offset:8192
	ds_read_b128 v[94:97], v186 offset:8192
	ds_read_b128 v[82:85], v185 offset:10240
	ds_read_b128 v[86:89], v186 offset:10240
	ds_read_b128 v[74:77], v185 offset:12288
	ds_read_b128 v[78:81], v186 offset:12288
	ds_read_b128 v[66:69], v185 offset:14336
	ds_read_b128 v[70:73], v186 offset:14336
	s_waitcnt lgkmcnt(8)
	v_mfma_scale_f32_32x32x64_f8f6f4 v[98:113], v[222:229], v[130:137], v[98:113], v194, v193 op_sel_hi:[0,0,0]
	v_mov_b32_e32 v0, v219
	s_nop 1
	v_permlane32_swap_b32_e32 v219, v0
	v_add_f32_e32 v219, v219, v0
	v_fma_f32 v209, v209, v218, v219
	v_max_f32_e32 v177, v114, v115
	v_max3_f32 v177, v177, v116, v117
	v_max3_f32 v177, v177, v118, v119
	v_max3_f32 v177, v177, v120, v121
	v_max3_f32 v177, v177, v122, v123
	v_max3_f32 v177, v177, v124, v125
	v_max3_f32 v177, v177, v126, v127
	v_max3_f32 v177, v177, v128, v129
	s_waitcnt lgkmcnt(6)
	v_mfma_scale_f32_32x32x64_f8f6f4 v[50:65], v[246:253], v[90:97], v[50:65], v194, v194 op_sel_hi:[0,0,0]
	s_waitcnt vmcnt(0)
	ds_write_b128 v210, v[158:161]
	ds_write_b128 v211, v[162:165] offset:16384
	s_waitcnt lgkmcnt(6)
	v_mfma_scale_f32_32x32x64_f8f6f4 v[34:49], v[246:253], v[82:89], v[34:49], v194, v194 op_sel_hi:[0,0,0]
	s_waitcnt lgkmcnt(0)
	s_barrier
	global_load_dwordx4 v[158:161], v176, s[18:19]
	global_load_dwordx4 v[162:165], v178, s[16:17]
	v_add_u32_e32 v176, 0x2000, v176
	v_add_u32_e32 v178, 0x20000, v178
	v_max_f32_e32 v0, v98, v99
	v_max3_f32 v0, v0, v100, v101
	v_max3_f32 v0, v0, v102, v103
	v_max3_f32 v0, v0, v104, v105
	s_waitcnt lgkmcnt(2)
	v_mfma_scale_f32_32x32x64_f8f6f4 v[18:33], v[246:253], v[74:81], v[18:33], v194, v194 op_sel_hi:[0,0,0]
	v_max3_f32 v0, v0, v106, v107
	v_max3_f32 v0, v0, v108, v109
	v_max3_f32 v0, v0, v110, v111
	v_max3_f32 v0, v0, v112, v113
	s_waitcnt lgkmcnt(0)
	v_mfma_scale_f32_32x32x64_f8f6f4 v[2:17], v[246:253], v[66:73], v[2:17], v194, v194 op_sel_hi:[0,0,0]
	v_max_f32_e32 v177, v177, v0
	v_mov_b32_e32 v0, v177
	v_mov_b32_e32 v221, 1.0
	s_nop 0
	v_permlane32_swap_b32_e32 v177, v0
	v_max_f32_e32 v177, v177, v0
	v_cmp_ge_f32_e32 vcc, s90, v177
	s_cmp_eq_u64 vcc, exec
	s_cbranch_scc0 .Lmla_s4_newmax
; __device__ __forceinline__ void finishSM9(f32x16& p0, f32x16& p1, float alpha, float& l_reg, v8i32& p8) {
; #pragma unroll
;   for (int r = 0; r < 16; ++r) { p0[r] = __builtin_amdgcn_exp2f(p0[r]); p1[r] = __builtin_amdgcn_exp2f(p1[r]); }
;   float ps = 0;
; #pragma unroll
;   for (int r = 0; r < 16; ++r) ps += p0[r];
; #pragma unroll
;   for (int r = 0; r < 16; ++r) ps += p1[r];
;   { auto rr = __builtin_amdgcn_permlane32_swap(__float_as_uint(ps), __float_as_uint(ps), false, false);
;     ps = __uint_as_float(rr[0]) + __uint_as_float(rr[1]); }
;   l_reg = l_reg * alpha + ps;
; #pragma unroll
;   for (int g = 0; g < 4; ++g) {
;     int w = __builtin_amdgcn_cvt_pk_fp8_f32(p0[4 * g], p0[4 * g + 1], 0, false); p8[g] = __builtin_amdgcn_cvt_pk_fp8_f32(p0[4 * g + 2], p0[4 * g + 3], w, true);
;     int u = __builtin_amdgcn_cvt_pk_fp8_f32(p1[4 * g], p1[4 * g + 1], 0, false); p8[4 + g] = __builtin_amdgcn_cvt_pk_fp8_f32(p1[4 * g + 2], p1[4 * g + 3], u, true); }
; }
; __device__ __forceinline__ void pv8(f32x16* o, const char* Vt, const v8i32 p8, int r32, int hi) {
;   const int sw = (r32 >> 2) & 3, a0 = r32 * 64 + (((hi * 2) ^ sw) << 4), a1 = r32 * 64 + (((hi * 2 + 1) ^ sw) << 4);
; #pragma unroll
;   for (int d0 = 0; d0 < 4; ++d0) {
;     const v8i32 vf = cat8(*reinterpret_cast<const v4i32*>(Vt + d0 * 2048 + a0), *reinterpret_cast<const v4i32*>(Vt + d0 * 2048 + a1));
;     o[d0] = __builtin_amdgcn_mfma_scale_f32_32x32x64_f8f6f4(p8, vf, o[d0], 0, 0, 0, 127, 0, 127); }
; }
; __device__ __forceinline__ void qkt9(f32x16& p0, f32x16& p1, const char* Kn, const char* Kr, const v8i32* qf, const float init, int r32, int hi) {
; #pragma unroll
;   for (int r = 0; r < 16; ++r) { p0[r] = init; p1[r] = init; }
; #pragma unroll
;   for (int s = 0; s < 2; ++s) { const int c0 = s * 4 + hi * 2;
;     const v8i32 a0 = cat8(*reinterpret_cast<const v4i32*>(Kn + KN8SW(r32, c0)), *reinterpret_cast<const v4i32*>(Kn + KN8SW(r32, c0 + 1)));
;     const v8i32 a1 = cat8(*reinterpret_cast<const v4i32*>(Kn + 4096 + KN8SW(r32, c0)), *reinterpret_cast<const v4i32*>(Kn + 4096 + KN8SW(r32, c0 + 1)));
;     p0 = __builtin_amdgcn_mfma_scale_f32_32x32x64_f8f6f4(a0, qf[s], p0, 0, 0, 0, 127, 0, 124);
;     p1 = __builtin_amdgcn_mfma_scale_f32_32x32x64_f8f6f4(a1, qf[s], p1, 0, 0, 0, 127, 0, 124); }
;   { const int c0 = hi * 2;
.Lmla_s4_cont:
	ds_read_b128 v[82:85], v215 offset:16384
	ds_read_b128 v[86:89], v216 offset:16384
	ds_read_b128 v[222:225], v215 offset:20480
	ds_read_b128 v[226:229], v216 offset:20480
	v_exp_f32_e32 v0, v114
	v_exp_f32_e32 v177, v115
	v_exp_f32_e32 v179, v116
	v_exp_f32_e32 v254, v117
	v_add_f32_e32 v219, v0, v177
	v_cvt_pk_fp8_f32 v246, v0, v177
	v_add_f32_e32 v219, v179, v219
	v_add_f32_e32 v219, v254, v219
	v_cvt_pk_fp8_f32 v246, v179, v254 op_sel:[0,0,1]
	s_waitcnt lgkmcnt(2)
	v_mfma_scale_f32_32x32x64_f8f6f4 v[82:97], v[82:89], v[146:153], v[230:245], v194, v193 op_sel_hi:[0,0,0]
	v_exp_f32_e32 v0, v118
	v_exp_f32_e32 v177, v119
	v_exp_f32_e32 v179, v120
	v_exp_f32_e32 v254, v121
	v_add_f32_e32 v219, v0, v219
	v_add_f32_e32 v219, v177, v219
	v_cvt_pk_fp8_f32 v247, v0, v177
	v_add_f32_e32 v219, v179, v219
	v_add_f32_e32 v219, v254, v219
	v_cvt_pk_fp8_f32 v247, v179, v254 op_sel:[0,0,1]
	ds_read_b128 v[114:117], v213 offset:16384
	ds_read_b128 v[118:121], v214 offset:16384
	s_waitcnt lgkmcnt(2)
	v_mfma_scale_f32_32x32x64_f8f6f4 v[66:81], v[222:229], v[146:153], v[230:245], v194, v193 op_sel_hi:[0,0,0]
	ds_read_b128 v[222:225], v213 offset:20480
	ds_read_b128 v[226:229], v214 offset:20480
	v_exp_f32_e32 v0, v122
	v_exp_f32_e32 v177, v123
	v_exp_f32_e32 v179, v124
	v_exp_f32_e32 v254, v125
	v_add_f32_e32 v219, v0, v219
	v_add_f32_e32 v219, v177, v219
	v_cvt_pk_fp8_f32 v248, v0, v177
	v_add_f32_e32 v219, v179, v219
	v_add_f32_e32 v219, v254, v219
	v_cvt_pk_fp8_f32 v248, v179, v254 op_sel:[0,0,1]
	v_exp_f32_e32 v0, v126
	v_exp_f32_e32 v177, v127
	v_exp_f32_e32 v179, v128
	v_exp_f32_e32 v254, v129
	v_add_f32_e32 v219, v0, v219
	v_add_f32_e32 v219, v177, v219
	v_cvt_pk_fp8_f32 v249, v0, v177
	v_add_f32_e32 v219, v179, v219
	v_add_f32_e32 v219, v254, v219
	v_cvt_pk_fp8_f32 v249, v179, v254 op_sel:[0,0,1]
	ds_read_b128 v[122:125], v185 offset:32768
	ds_read_b128 v[126:129], v186 offset:32768
	s_waitcnt lgkmcnt(4)
	v_mfma_scale_f32_32x32x64_f8f6f4 v[82:97], v[114:121], v[138:145], v[82:97], v194, v193 op_sel_hi:[0,0,0]
	v_exp_f32_e32 v0, v98
	v_exp_f32_e32 v177, v99
	v_exp_f32_e32 v179, v100
	v_exp_f32_e32 v254, v101
	v_add_f32_e32 v219, v0, v219
	v_add_f32_e32 v219, v177, v219
	v_cvt_pk_fp8_f32 v250, v0, v177
	v_add_f32_e32 v219, v179, v219
	v_add_f32_e32 v219, v254, v219
	v_cvt_pk_fp8_f32 v250, v179, v254 op_sel:[0,0,1]
	s_waitcnt lgkmcnt(2)
	v_mfma_scale_f32_32x32x64_f8f6f4 v[66:81], v[222:229], v[138:145], v[66:81], v194, v193 op_sel_hi:[0,0,0]
	ds_read_b128 v[222:225], v185 offset:34816
	ds_read_b128 v[226:229], v186 offset:34816
	v_exp_f32_e32 v0, v102
	v_exp_f32_e32 v177, v103
	v_exp_f32_e32 v179, v104
	v_exp_f32_e32 v254, v105
	v_add_f32_e32 v219, v0, v219
	v_add_f32_e32 v219, v177, v219
	v_cvt_pk_fp8_f32 v251, v0, v177
	v_add_f32_e32 v219, v179, v219
	v_add_f32_e32 v219, v254, v219
	v_cvt_pk_fp8_f32 v251, v179, v254 op_sel:[0,0,1]
	v_exp_f32_e32 v0, v106
	v_exp_f32_e32 v177, v107
	v_exp_f32_e32 v179, v108
	v_exp_f32_e32 v254, v109
	v_add_f32_e32 v219, v0, v219
	v_add_f32_e32 v219, v177, v219
	v_cvt_pk_fp8_f32 v252, v0, v177
	v_add_f32_e32 v219, v179, v219
	v_add_f32_e32 v219, v254, v219
	v_cvt_pk_fp8_f32 v252, v179, v254 op_sel:[0,0,1]
	s_waitcnt lgkmcnt(2)
	v_mfma_scale_f32_32x32x64_f8f6f4 v[82:97], v[122:129], v[130:137], v[82:97], v194, v193 op_sel_hi:[0,0,0]
	v_exp_f32_e32 v0, v110
	v_exp_f32_e32 v177, v111
	v_exp_f32_e32 v179, v112
	v_exp_f32_e32 v254, v113
	v_add_f32_e32 v219, v0, v219
	v_add_f32_e32 v219, v177, v219
	v_cvt_pk_fp8_f32 v253, v0, v177
	v_add_f32_e32 v219, v179, v219
	v_add_f32_e32 v219, v254, v219
	v_cvt_pk_fp8_f32 v253, v179, v254 op_sel:[0,0,1]
	ds_read_b128 v[122:125], v185 offset:43008
	ds_read_b128 v[126:129], v186 offset:43008
	ds_read_b128 v[114:117], v185 offset:45056
	ds_read_b128 v[118:121], v186 offset:45056
	ds_read_b128 v[106:109], v185 offset:47104
	ds_read_b128 v[110:113], v186 offset:47104
	ds_read_b128 v[98:101], v185 offset:49152
	ds_read_b128 v[102:105], v186 offset:49152
	s_waitcnt lgkmcnt(8)
	v_mfma_scale_f32_32x32x64_f8f6f4 v[66:81], v[222:229], v[130:137], v[66:81], v194, v193 op_sel_hi:[0,0,0]
	v_mov_b32_e32 v0, v219
	s_nop 1
	v_permlane32_swap_b32_e32 v219, v0
	v_add_f32_e32 v219, v219, v0
	v_fma_f32 v209, v209, v221, v219
	v_max_f32_e32 v177, v82, v83
	v_max3_f32 v177, v177, v84, v85
	v_max3_f32 v177, v177, v86, v87
	v_max3_f32 v177, v177, v88, v89
	v_max3_f32 v177, v177, v90, v91
	v_max3_f32 v177, v177, v92, v93
	v_max3_f32 v177, v177, v94, v95
	v_max3_f32 v177, v177, v96, v97
	s_waitcnt lgkmcnt(6)
	v_mfma_scale_f32_32x32x64_f8f6f4 v[50:65], v[246:253], v[122:129], v[50:65], v194, v194 op_sel_hi:[0,0,0]
	s_waitcnt vmcnt(0)
	ds_write_b128 v210, v[158:161] offset:8192
	ds_write_b128 v211, v[162:165] offset:24576
	s_waitcnt lgkmcnt(6)
	v_mfma_scale_f32_32x32x64_f8f6f4 v[34:49], v[246:253], v[114:121], v[34:49], v194, v194 op_sel_hi:[0,0,0]
	s_waitcnt lgkmcnt(0)
	s_barrier
	global_load_dwordx4 v[158:161], v176, s[18:19]
	global_load_dwordx4 v[162:165], v178, s[16:17]
	v_add_u32_e32 v176, 0x2000, v176
	v_add_u32_e32 v178, 0x20000, v178
	v_max_f32_e32 v0, v66, v67
	v_max3_f32 v0, v0, v68, v69
	v_max3_f32 v0, v0, v70, v71
	v_max3_f32 v0, v0, v72, v73
	s_waitcnt lgkmcnt(2)
	v_mfma_scale_f32_32x32x64_f8f6f4 v[18:33], v[246:253], v[106:113], v[18:33], v194, v194 op_sel_hi:[0,0,0]
	v_max3_f32 v0, v0, v74, v75
	v_max3_f32 v0, v0, v76, v77
	v_max3_f32 v0, v0, v78, v79
	v_max3_f32 v0, v0, v80, v81
	s_waitcnt lgkmcnt(0)
	v_mfma_scale_f32_32x32x64_f8f6f4 v[2:17], v[246:253], v[98:105], v[2:17], v194, v194 op_sel_hi:[0,0,0]
	v_max_f32_e32 v177, v177, v0
	v_mov_b32_e32 v0, v177
	v_mov_b32_e32 v218, 1.0
	s_nop 0
	v_permlane32_swap_b32_e32 v177, v0
	v_max_f32_e32 v177, v177, v0
	v_cmp_ge_f32_e32 vcc, s90, v177
	s_cmp_eq_u64 vcc, exec
	s_cbranch_scc0 .Lmla_s5_newmax
; __device__ __forceinline__ void finishSM9(f32x16& p0, f32x16& p1, float alpha, float& l_reg, v8i32& p8) {
; #pragma unroll
;   for (int r = 0; r < 16; ++r) { p0[r] = __builtin_amdgcn_exp2f(p0[r]); p1[r] = __builtin_amdgcn_exp2f(p1[r]); }
;   float ps = 0;
; #pragma unroll
;   for (int r = 0; r < 16; ++r) ps += p0[r];
; #pragma unroll
;   for (int r = 0; r < 16; ++r) ps += p1[r];
;   { auto rr = __builtin_amdgcn_permlane32_swap(__float_as_uint(ps), __float_as_uint(ps), false, false);
;     ps = __uint_as_float(rr[0]) + __uint_as_float(rr[1]); }
;   l_reg = l_reg * alpha + ps;
; #pragma unroll
;   for (int g = 0; g < 4; ++g) {
;     int w = __builtin_amdgcn_cvt_pk_fp8_f32(p0[4 * g], p0[4 * g + 1], 0, false); p8[g] = __builtin_amdgcn_cvt_pk_fp8_f32(p0[4 * g + 2], p0[4 * g + 3], w, true);
;     int u = __builtin_amdgcn_cvt_pk_fp8_f32(p1[4 * g], p1[4 * g + 1], 0, false); p8[4 + g] = __builtin_amdgcn_cvt_pk_fp8_f32(p1[4 * g + 2], p1[4 * g + 3], u, true); }
; }
; __device__ __forceinline__ void pv8(f32x16* o, const char* Vt, const v8i32 p8, int r32, int hi) {
;   const int sw = (r32 >> 2) & 3, a0 = r32 * 64 + (((hi * 2) ^ sw) << 4), a1 = r32 * 64 + (((hi * 2 + 1) ^ sw) << 4);
; #pragma unroll
;   for (int d0 = 0; d0 < 4; ++d0) {
;     const v8i32 vf = cat8(*reinterpret_cast<const v4i32*>(Vt + d0 * 2048 + a0), *reinterpret_cast<const v4i32*>(Vt + d0 * 2048 + a1));
;     o[d0] = __builtin_amdgcn_mfma_scale_f32_32x32x64_f8f6f4(p8, vf, o[d0], 0, 0, 0, 127, 0, 127); }
; }
; __device__ __forceinline__ void qkt9(f32x16& p0, f32x16& p1, const char* Kn, const char* Kr, const v8i32* qf, const float init, int r32, int hi) {
; #pragma unroll
;   for (int r = 0; r < 16; ++r) { p0[r] = init; p1[r] = init; }
; #pragma unroll
;   for (int s = 0; s < 2; ++s) { const int c0 = s * 4 + hi * 2;
;     const v8i32 a0 = cat8(*reinterpret_cast<const v4i32*>(Kn + KN8SW(r32, c0)), *reinterpret_cast<const v4i32*>(Kn + KN8SW(r32, c0 + 1)));
;     const v8i32 a1 = cat8(*reinterpret_cast<const v4i32*>(Kn + 4096 + KN8SW(r32, c0)), *reinterpret_cast<const v4i32*>(Kn + 4096 + KN8SW(r32, c0 + 1)));
;     p0 = __builtin_amdgcn_mfma_scale_f32_32x32x64_f8f6f4(a0, qf[s], p0, 0, 0, 0, 127, 0, 124);
;     p1 = __builtin_amdgcn_mfma_scale_f32_32x32x64_f8f6f4(a1, qf[s], p1, 0, 0, 0, 127, 0, 124); }
;   { const int c0 = hi * 2;
.Lmla_s5_cont:
	s_add_i32 s30, s30, 1
	s_cmpk_lt_u32 s30, 42
	s_cbranch_scc1 .Lmla_stag_loop
	ds_read_b128 v[114:117], v215 offset:24576
	ds_read_b128 v[118:121], v216 offset:24576
	ds_read_b128 v[222:225], v215 offset:28672
	ds_read_b128 v[226:229], v216 offset:28672
	v_exp_f32_e32 v0, v82
	v_exp_f32_e32 v177, v83
	v_exp_f32_e32 v179, v84
	v_exp_f32_e32 v254, v85
	v_add_f32_e32 v219, v0, v177
	v_cvt_pk_fp8_f32 v246, v0, v177
	v_add_f32_e32 v219, v179, v219
	v_add_f32_e32 v219, v254, v219
	v_cvt_pk_fp8_f32 v246, v179, v254 op_sel:[0,0,1]
	s_waitcnt lgkmcnt(2)
	v_mfma_scale_f32_32x32x64_f8f6f4 v[114:129], v[114:121], v[146:153], v[230:245], v194, v193 op_sel_hi:[0,0,0]
	v_exp_f32_e32 v0, v86
	v_exp_f32_e32 v177, v87
	v_exp_f32_e32 v179, v88
	v_exp_f32_e32 v254, v89
	v_add_f32_e32 v219, v0, v219
	v_add_f32_e32 v219, v177, v219
	v_cvt_pk_fp8_f32 v247, v0, v177
	v_add_f32_e32 v219, v179, v219
	v_add_f32_e32 v219, v254, v219
	v_cvt_pk_fp8_f32 v247, v179, v254 op_sel:[0,0,1]
	ds_read_b128 v[82:85], v213 offset:24576
	ds_read_b128 v[86:89], v214 offset:24576
	s_waitcnt lgkmcnt(2)
	v_mfma_scale_f32_32x32x64_f8f6f4 v[98:113], v[222:229], v[146:153], v[230:245], v194, v193 op_sel_hi:[0,0,0]
	ds_read_b128 v[222:225], v213 offset:28672
	ds_read_b128 v[226:229], v214 offset:28672
	v_exp_f32_e32 v0, v90
	v_exp_f32_e32 v177, v91
	v_exp_f32_e32 v179, v92
	v_exp_f32_e32 v254, v93
	v_add_f32_e32 v219, v0, v219
	v_add_f32_e32 v219, v177, v219
	v_cvt_pk_fp8_f32 v248, v0, v177
	v_add_f32_e32 v219, v179, v219
	v_add_f32_e32 v219, v254, v219
	v_cvt_pk_fp8_f32 v248, v179, v254 op_sel:[0,0,1]
	v_exp_f32_e32 v0, v94
	v_exp_f32_e32 v177, v95
	v_exp_f32_e32 v179, v96
	v_exp_f32_e32 v254, v97
	v_add_f32_e32 v219, v0, v219
	v_add_f32_e32 v219, v177, v219
	v_cvt_pk_fp8_f32 v249, v0, v177
	v_add_f32_e32 v219, v179, v219
	v_add_f32_e32 v219, v254, v219
	v_cvt_pk_fp8_f32 v249, v179, v254 op_sel:[0,0,1]
	ds_read_b128 v[90:93], v185 offset:36864
	ds_read_b128 v[94:97], v186 offset:36864
	s_waitcnt lgkmcnt(4)
	v_mfma_scale_f32_32x32x64_f8f6f4 v[114:129], v[82:89], v[138:145], v[114:129], v194, v193 op_sel_hi:[0,0,0]
	v_exp_f32_e32 v0, v66
	v_exp_f32_e32 v177, v67
	v_exp_f32_e32 v179, v68
	v_exp_f32_e32 v254, v69
	v_add_f32_e32 v219, v0, v219
	v_add_f32_e32 v219, v177, v219
	v_cvt_pk_fp8_f32 v250, v0, v177
	v_add_f32_e32 v219, v179, v219
	v_add_f32_e32 v219, v254, v219
	v_cvt_pk_fp8_f32 v250, v179, v254 op_sel:[0,0,1]
	s_waitcnt lgkmcnt(2)
	v_mfma_scale_f32_32x32x64_f8f6f4 v[98:113], v[222:229], v[138:145], v[98:113], v194, v193 op_sel_hi:[0,0,0]
	ds_read_b128 v[222:225], v185 offset:38912
	ds_read_b128 v[226:229], v186 offset:38912
	v_exp_f32_e32 v0, v70
	v_exp_f32_e32 v177, v71
	v_exp_f32_e32 v179, v72
	v_exp_f32_e32 v254, v73
	v_add_f32_e32 v219, v0, v219
	v_add_f32_e32 v219, v177, v219
	v_cvt_pk_fp8_f32 v251, v0, v177
	v_add_f32_e32 v219, v179, v219
	v_add_f32_e32 v219, v254, v219
	v_cvt_pk_fp8_f32 v251, v179, v254 op_sel:[0,0,1]
	v_exp_f32_e32 v0, v74
	v_exp_f32_e32 v177, v75
	v_exp_f32_e32 v179, v76
	v_exp_f32_e32 v254, v77
	v_add_f32_e32 v219, v0, v219
	v_add_f32_e32 v219, v177, v219
	v_cvt_pk_fp8_f32 v252, v0, v177
	v_add_f32_e32 v219, v179, v219
	v_add_f32_e32 v219, v254, v219
	v_cvt_pk_fp8_f32 v252, v179, v254 op_sel:[0,0,1]
	s_waitcnt lgkmcnt(2)
	v_mfma_scale_f32_32x32x64_f8f6f4 v[114:129], v[90:97], v[130:137], v[114:129], v194, v193 op_sel_hi:[0,0,0]
	v_exp_f32_e32 v0, v78
	v_exp_f32_e32 v177, v79
	v_exp_f32_e32 v179, v80
	v_exp_f32_e32 v254, v81
	v_add_f32_e32 v219, v0, v219
	v_add_f32_e32 v219, v177, v219
	v_cvt_pk_fp8_f32 v253, v0, v177
	v_add_f32_e32 v219, v179, v219
	v_add_f32_e32 v219, v254, v219
	v_cvt_pk_fp8_f32 v253, v179, v254 op_sel:[0,0,1]
	ds_read_b128 v[90:93], v185 offset:0
	ds_read_b128 v[94:97], v186 offset:0
	ds_read_b128 v[82:85], v185 offset:2048
	ds_read_b128 v[86:89], v186 offset:2048
	ds_read_b128 v[74:77], v185 offset:4096
	ds_read_b128 v[78:81], v186 offset:4096
	ds_read_b128 v[66:69], v185 offset:6144
	ds_read_b128 v[70:73], v186 offset:6144
	s_waitcnt lgkmcnt(8)
	v_mfma_scale_f32_32x32x64_f8f6f4 v[98:113], v[222:229], v[130:137], v[98:113], v194, v193 op_sel_hi:[0,0,0]
	v_mov_b32_e32 v0, v219
	s_nop 1
	v_permlane32_swap_b32_e32 v219, v0
	v_add_f32_e32 v219, v219, v0
	v_fma_f32 v209, v209, v218, v219
	v_max_f32_e32 v177, v114, v115
	v_max3_f32 v177, v177, v116, v117
	v_max3_f32 v177, v177, v118, v119
	v_max3_f32 v177, v177, v120, v121
	v_max3_f32 v177, v177, v122, v123
	v_max3_f32 v177, v177, v124, v125
	v_max3_f32 v177, v177, v126, v127
	v_max3_f32 v177, v177, v128, v129
	s_waitcnt lgkmcnt(6)
	v_mfma_scale_f32_32x32x64_f8f6f4 v[50:65], v[246:253], v[90:97], v[50:65], v194, v194 op_sel_hi:[0,0,0]
	s_waitcnt vmcnt(0)
	ds_write_b128 v210, v[158:161] offset:43008
	ds_write_b128 v211, v[162:165] offset:51200
	s_waitcnt lgkmcnt(6)
	v_mfma_scale_f32_32x32x64_f8f6f4 v[34:49], v[246:253], v[82:89], v[34:49], v194, v194 op_sel_hi:[0,0,0]
	s_waitcnt lgkmcnt(0)
	s_barrier
	global_load_dwordx4 v[158:161], v176, s[18:19]
	global_load_dwordx4 v[162:165], v178, s[16:17]
	v_add_u32_e32 v176, 0x2000, v176
	v_add_u32_e32 v178, 0x20000, v178
	v_max_f32_e32 v0, v98, v99
	v_max3_f32 v0, v0, v100, v101
	v_max3_f32 v0, v0, v102, v103
	v_max3_f32 v0, v0, v104, v105
	s_waitcnt lgkmcnt(2)
	v_mfma_scale_f32_32x32x64_f8f6f4 v[18:33], v[246:253], v[74:81], v[18:33], v194, v194 op_sel_hi:[0,0,0]
	v_max3_f32 v0, v0, v106, v107
	v_max3_f32 v0, v0, v108, v109
	v_max3_f32 v0, v0, v110, v111
	v_max3_f32 v0, v0, v112, v113
	s_waitcnt lgkmcnt(0)
	v_mfma_scale_f32_32x32x64_f8f6f4 v[2:17], v[246:253], v[66:73], v[2:17], v194, v194 op_sel_hi:[0,0,0]
	v_max_f32_e32 v177, v177, v0
	v_mov_b32_e32 v0, v177
	v_mov_b32_e32 v221, 1.0
	s_nop 0
	v_permlane32_swap_b32_e32 v177, v0
	v_max_f32_e32 v177, v177, v0
	v_cmp_ge_f32_e32 vcc, s90, v177
	s_cmp_eq_u64 vcc, exec
	s_cbranch_scc0 .Lmla_q0_newmax
; __device__ __forceinline__ void finishSM9(f32x16& p0, f32x16& p1, float alpha, float& l_reg, v8i32& p8) {
; #pragma unroll
;   for (int r = 0; r < 16; ++r) { p0[r] = __builtin_amdgcn_exp2f(p0[r]); p1[r] = __builtin_amdgcn_exp2f(p1[r]); }
;   float ps = 0;
; #pragma unroll
;   for (int r = 0; r < 16; ++r) ps += p0[r];
; #pragma unroll
;   for (int r = 0; r < 16; ++r) ps += p1[r];
;   { auto rr = __builtin_amdgcn_permlane32_swap(__float_as_uint(ps), __float_as_uint(ps), false, false);
;     ps = __uint_as_float(rr[0]) + __uint_as_float(rr[1]); }
;   l_reg = l_reg * alpha + ps;
; #pragma unroll
;   for (int g = 0; g < 4; ++g) {
;     int w = __builtin_amdgcn_cvt_pk_fp8_f32(p0[4 * g], p0[4 * g + 1], 0, false); p8[g] = __builtin_amdgcn_cvt_pk_fp8_f32(p0[4 * g + 2], p0[4 * g + 3], w, true);
;     int u = __builtin_amdgcn_cvt_pk_fp8_f32(p1[4 * g], p1[4 * g + 1], 0, false); p8[4 + g] = __builtin_amdgcn_cvt_pk_fp8_f32(p1[4 * g + 2], p1[4 * g + 3], u, true); }
; }
; __device__ __forceinline__ void pv8(f32x16* o, const char* Vt, const v8i32 p8, int r32, int hi) {
;   const int sw = (r32 >> 2) & 3, a0 = r32 * 64 + (((hi * 2) ^ sw) << 4), a1 = r32 * 64 + (((hi * 2 + 1) ^ sw) << 4);
; #pragma unroll
;   for (int d0 = 0; d0 < 4; ++d0) {
;     const v8i32 vf = cat8(*reinterpret_cast<const v4i32*>(Vt + d0 * 2048 + a0), *reinterpret_cast<const v4i32*>(Vt + d0 * 2048 + a1));
;     o[d0] = __builtin_amdgcn_mfma_scale_f32_32x32x64_f8f6f4(p8, vf, o[d0], 0, 0, 0, 127, 0, 127); }
; }
; __device__ __forceinline__ void qkt9(f32x16& p0, f32x16& p1, const char* Kn, const char* Kr, const v8i32* qf, const float init, int r32, int hi) {
; #pragma unroll
;   for (int r = 0; r < 16; ++r) { p0[r] = init; p1[r] = init; }
; #pragma unroll
;   for (int s = 0; s < 2; ++s) { const int c0 = s * 4 + hi * 2;
;     const v8i32 a0 = cat8(*reinterpret_cast<const v4i32*>(Kn + KN8SW(r32, c0)), *reinterpret_cast<const v4i32*>(Kn + KN8SW(r32, c0 + 1)));
;     const v8i32 a1 = cat8(*reinterpret_cast<const v4i32*>(Kn + 4096 + KN8SW(r32, c0)), *reinterpret_cast<const v4i32*>(Kn + 4096 + KN8SW(r32, c0 + 1)));
;     p0 = __builtin_amdgcn_mfma_scale_f32_32x32x64_f8f6f4(a0, qf[s], p0, 0, 0, 0, 127, 0, 124);
;     p1 = __builtin_amdgcn_mfma_scale_f32_32x32x64_f8f6f4(a1, qf[s], p1, 0, 0, 0, 127, 0, 124); }
;   { const int c0 = hi * 2;
.Lmla_q0_cont:
	ds_read_b128 v[82:85], v215 offset:51200
	ds_read_b128 v[86:89], v216 offset:51200
	ds_read_b128 v[222:225], v215 offset:55296
	ds_read_b128 v[226:229], v216 offset:55296
	v_exp_f32_e32 v0, v114
	v_exp_f32_e32 v177, v115
	v_exp_f32_e32 v179, v116
	v_exp_f32_e32 v254, v117
	v_add_f32_e32 v219, v0, v177
	v_cvt_pk_fp8_f32 v246, v0, v177
	v_add_f32_e32 v219, v179, v219
	v_add_f32_e32 v219, v254, v219
	v_cvt_pk_fp8_f32 v246, v179, v254 op_sel:[0,0,1]
	s_waitcnt lgkmcnt(2)
	v_mfma_scale_f32_32x32x64_f8f6f4 v[82:97], v[82:89], v[146:153], v[230:245], v194, v193 op_sel_hi:[0,0,0]
	v_exp_f32_e32 v0, v118
	v_exp_f32_e32 v177, v119
	v_exp_f32_e32 v179, v120
	v_exp_f32_e32 v254, v121
	v_add_f32_e32 v219, v0, v219
	v_add_f32_e32 v219, v177, v219
	v_cvt_pk_fp8_f32 v247, v0, v177
	v_add_f32_e32 v219, v179, v219
	v_add_f32_e32 v219, v254, v219
	v_cvt_pk_fp8_f32 v247, v179, v254 op_sel:[0,0,1]
	ds_read_b128 v[114:117], v213 offset:51200
	ds_read_b128 v[118:121], v214 offset:51200
	s_waitcnt lgkmcnt(2)
	v_mfma_scale_f32_32x32x64_f8f6f4 v[66:81], v[222:229], v[146:153], v[230:245], v194, v193 op_sel_hi:[0,0,0]
	ds_read_b128 v[222:225], v213 offset:55296
	ds_read_b128 v[226:229], v214 offset:55296
	v_exp_f32_e32 v0, v122
	v_exp_f32_e32 v177, v123
	v_exp_f32_e32 v179, v124
	v_exp_f32_e32 v254, v125
	v_add_f32_e32 v219, v0, v219
	v_add_f32_e32 v219, v177, v219
	v_cvt_pk_fp8_f32 v248, v0, v177
	v_add_f32_e32 v219, v179, v219
	v_add_f32_e32 v219, v254, v219
	v_cvt_pk_fp8_f32 v248, v179, v254 op_sel:[0,0,1]
	v_exp_f32_e32 v0, v126
	v_exp_f32_e32 v177, v127
	v_exp_f32_e32 v179, v128
	v_exp_f32_e32 v254, v129
	v_add_f32_e32 v219, v0, v219
	v_add_f32_e32 v219, v177, v219
	v_cvt_pk_fp8_f32 v249, v0, v177
	v_add_f32_e32 v219, v179, v219
	v_add_f32_e32 v219, v254, v219
	v_cvt_pk_fp8_f32 v249, v179, v254 op_sel:[0,0,1]
	ds_read_b128 v[122:125], v185 offset:59392
	ds_read_b128 v[126:129], v186 offset:59392
	s_waitcnt lgkmcnt(4)
	v_mfma_scale_f32_32x32x64_f8f6f4 v[82:97], v[114:121], v[138:145], v[82:97], v194, v193 op_sel_hi:[0,0,0]
	v_exp_f32_e32 v0, v98
	v_exp_f32_e32 v177, v99
	v_exp_f32_e32 v179, v100
	v_exp_f32_e32 v254, v101
	v_add_f32_e32 v219, v0, v219
	v_add_f32_e32 v219, v177, v219
	v_cvt_pk_fp8_f32 v250, v0, v177
	v_add_f32_e32 v219, v179, v219
	v_add_f32_e32 v219, v254, v219
	v_cvt_pk_fp8_f32 v250, v179, v254 op_sel:[0,0,1]
	s_waitcnt lgkmcnt(2)
	v_mfma_scale_f32_32x32x64_f8f6f4 v[66:81], v[222:229], v[138:145], v[66:81], v194, v193 op_sel_hi:[0,0,0]
	ds_read_b128 v[222:225], v185 offset:61440
	ds_read_b128 v[226:229], v186 offset:61440
	v_exp_f32_e32 v0, v102
	v_exp_f32_e32 v177, v103
	v_exp_f32_e32 v179, v104
	v_exp_f32_e32 v254, v105
	v_add_f32_e32 v219, v0, v219
	v_add_f32_e32 v219, v177, v219
	v_cvt_pk_fp8_f32 v251, v0, v177
	v_add_f32_e32 v219, v179, v219
	v_add_f32_e32 v219, v254, v219
	v_cvt_pk_fp8_f32 v251, v179, v254 op_sel:[0,0,1]
	v_exp_f32_e32 v0, v106
	v_exp_f32_e32 v177, v107
	v_exp_f32_e32 v179, v108
	v_exp_f32_e32 v254, v109
	v_add_f32_e32 v219, v0, v219
	v_add_f32_e32 v219, v177, v219
	v_cvt_pk_fp8_f32 v252, v0, v177
	v_add_f32_e32 v219, v179, v219
	v_add_f32_e32 v219, v254, v219
	v_cvt_pk_fp8_f32 v252, v179, v254 op_sel:[0,0,1]
	s_waitcnt lgkmcnt(2)
	v_mfma_scale_f32_32x32x64_f8f6f4 v[82:97], v[122:129], v[130:137], v[82:97], v194, v193 op_sel_hi:[0,0,0]
	v_exp_f32_e32 v0, v110
	v_exp_f32_e32 v177, v111
	v_exp_f32_e32 v179, v112
	v_exp_f32_e32 v254, v113
	v_add_f32_e32 v219, v0, v219
	v_add_f32_e32 v219, v177, v219
	v_cvt_pk_fp8_f32 v253, v0, v177
	v_add_f32_e32 v219, v179, v219
	v_add_f32_e32 v219, v254, v219
	v_cvt_pk_fp8_f32 v253, v179, v254 op_sel:[0,0,1]
	ds_read_b128 v[122:125], v185 offset:8192
	ds_read_b128 v[126:129], v186 offset:8192
	ds_read_b128 v[114:117], v185 offset:10240
	ds_read_b128 v[118:121], v186 offset:10240
	ds_read_b128 v[106:109], v185 offset:12288
	ds_read_b128 v[110:113], v186 offset:12288
	ds_read_b128 v[98:101], v185 offset:14336
	ds_read_b128 v[102:105], v186 offset:14336
	s_waitcnt lgkmcnt(8)
	v_mfma_scale_f32_32x32x64_f8f6f4 v[66:81], v[222:229], v[130:137], v[66:81], v194, v193 op_sel_hi:[0,0,0]
	v_mov_b32_e32 v0, v219
	s_nop 1
	v_permlane32_swap_b32_e32 v219, v0
	v_add_f32_e32 v219, v219, v0
	v_fma_f32 v209, v209, v221, v219
	v_max_f32_e32 v177, v82, v83
	v_max3_f32 v177, v177, v84, v85
	v_max3_f32 v177, v177, v86, v87
	v_max3_f32 v177, v177, v88, v89
	v_max3_f32 v177, v177, v90, v91
	v_max3_f32 v177, v177, v92, v93
	v_max3_f32 v177, v177, v94, v95
	v_max3_f32 v177, v177, v96, v97
	s_waitcnt lgkmcnt(6)
	v_mfma_scale_f32_32x32x64_f8f6f4 v[50:65], v[246:253], v[122:129], v[50:65], v194, v194 op_sel_hi:[0,0,0]
	s_waitcnt vmcnt(0)
	ds_write_b128 v210, v[158:161]
	ds_write_b128 v211, v[162:165] offset:16384
	s_waitcnt lgkmcnt(6)
	v_mfma_scale_f32_32x32x64_f8f6f4 v[34:49], v[246:253], v[114:121], v[34:49], v194, v194 op_sel_hi:[0,0,0]
	s_waitcnt lgkmcnt(0)
	s_barrier
	v_max_f32_e32 v0, v66, v67
	v_max3_f32 v0, v0, v68, v69
	v_max3_f32 v0, v0, v70, v71
	v_max3_f32 v0, v0, v72, v73
	s_waitcnt lgkmcnt(2)
	v_mfma_scale_f32_32x32x64_f8f6f4 v[18:33], v[246:253], v[106:113], v[18:33], v194, v194 op_sel_hi:[0,0,0]
	v_max3_f32 v0, v0, v74, v75
	v_max3_f32 v0, v0, v76, v77
	v_max3_f32 v0, v0, v78, v79
	v_max3_f32 v0, v0, v80, v81
	s_waitcnt lgkmcnt(0)
	v_mfma_scale_f32_32x32x64_f8f6f4 v[2:17], v[246:253], v[98:105], v[2:17], v194, v194 op_sel_hi:[0,0,0]
	v_max_f32_e32 v177, v177, v0
	v_mov_b32_e32 v0, v177
	v_mov_b32_e32 v218, 1.0
	s_nop 0
	v_permlane32_swap_b32_e32 v177, v0
	v_max_f32_e32 v177, v177, v0
	v_cmp_ge_f32_e32 vcc, s90, v177
	s_cmp_eq_u64 vcc, exec
	s_cbranch_scc0 .Lmla_q1_newmax
